# attention key-tile loops: the P*V fragment reads (one ds_read + full LDS wait per MFMA) are hoisted into v210.. ahead of the softmax exps; MFMAs run behind counted waits
# speedup vs baseline: 1.0089x; 1.0089x over previous
.LBB0_1035:
	s_add_i32 s12, s13, 1
	s_bitcmp1_b32 s13, 0
	s_cselect_b32 s13, 0x4800, 0
	v_or_b32_e32 v80, s13, v42
	v_add_u32_e32 v55, v80, v47
	ds_read_b128 v[56:59], v55
	ds_read_b128 v[60:63], v55 offset:64
	v_add_u32_e32 v84, v80, v53
	ds_read_b128 v[80:83], v84 offset:9216
	s_andn2_b64 vcc, exec, s[66:67]
	s_waitcnt lgkmcnt(2)
	v_mfma_f32_16x16x32_bf16 v[56:59], v[56:59], v[2:5], 0
	ds_read_b128 v[64:67], v55 offset:640
	ds_read_b128 v[68:71], v55 offset:4672
	ds_read_b128 v[72:75], v55 offset:5248
	s_waitcnt lgkmcnt(4)
	v_mfma_f32_16x16x32_bf16 v[56:59], v[60:63], v[6:9], v[56:59]
	ds_read_b128 v[60:63], v55 offset:576
	s_waitcnt lgkmcnt(0)
	v_mfma_f32_16x16x32_bf16 v[60:63], v[60:63], v[2:5], 0
	v_mfma_f32_16x16x32_bf16 v[60:63], v[64:67], v[6:9], v[60:63]
	ds_read_b128 v[64:67], v55 offset:4608
	s_waitcnt lgkmcnt(0)
	v_mfma_f32_16x16x32_bf16 v[64:67], v[64:67], v[2:5], 0
	v_mfma_f32_16x16x32_bf16 v[64:67], v[68:71], v[6:9], v[64:67]
	ds_read_b128 v[68:71], v55 offset:5184
	v_mul_f32_e32 v55, 0x3e38aa3b, v56
	s_waitcnt lgkmcnt(0)
	v_mfma_f32_16x16x32_bf16 v[68:71], v[68:71], v[2:5], 0
	v_mfma_f32_16x16x32_bf16 v[68:71], v[72:75], v[6:9], v[68:71]
	v_mul_f32_e32 v72, 0x3e38aa3b, v57
	v_max3_f32 v55, v55, s88, v72
	v_mul_f32_e32 v72, 0x3e38aa3b, v58
	v_mul_f32_e32 v73, 0x3e38aa3b, v59
	v_max3_f32 v55, v55, v72, v73
	v_mul_f32_e32 v72, 0x3e38aa3b, v60
	v_mul_f32_e32 v73, 0x3e38aa3b, v61
	v_max3_f32 v55, v55, v72, v73
	v_mul_f32_e32 v72, 0x3e38aa3b, v62
	v_mul_f32_e32 v73, 0x3e38aa3b, v63
	v_max3_f32 v55, v55, v72, v73
	v_mul_f32_e32 v72, 0x3e38aa3b, v64
	v_mul_f32_e32 v73, 0x3e38aa3b, v65
	v_max3_f32 v55, v55, v72, v73
	v_mul_f32_e32 v72, 0x3e38aa3b, v66
	v_mul_f32_e32 v73, 0x3e38aa3b, v67
	v_max3_f32 v55, v55, v72, v73
	v_mul_f32_e32 v72, 0x3e38aa3b, v68
	v_mul_f32_e32 v73, 0x3e38aa3b, v69
	v_max3_f32 v55, v55, v72, v73
	v_mul_f32_e32 v72, 0x3e38aa3b, v70
	v_mul_f32_e32 v73, 0x3e38aa3b, v71
	v_max3_f32 v55, v55, v72, v73
	ds_bpermute_b32 v72, v43, v55
	s_waitcnt lgkmcnt(0)
	v_max_f32_e32 v72, v72, v72
	v_max_f32_e32 v55, v55, v72
	ds_bpermute_b32 v72, v1, v55
	s_waitcnt lgkmcnt(0)
	ds_read_b128 v[210:213], v84 offset:11520
	ds_read_b128 v[214:217], v84 offset:11584
	ds_read_b128 v[218:221], v84 offset:13824
	ds_read_b128 v[222:225], v84 offset:13888
	ds_read_b128 v[226:229], v84 offset:16128
	ds_read_b128 v[230:233], v84 offset:16192
	v_max3_f32 v55, v52, v55, v72
	v_sub_f32_e32 v52, v52, v55
	v_fma_f32 v56, v56, s91, -v55
	v_fma_f32 v57, v57, s91, -v55
	v_fma_f32 v58, v58, s91, -v55
	v_fma_f32 v59, v59, s91, -v55
	v_fma_f32 v60, v60, s91, -v55
	v_fma_f32 v61, v61, s91, -v55
	v_fma_f32 v62, v62, s91, -v55
	v_fma_f32 v63, v63, s91, -v55
	v_exp_f32_e32 v52, v52
	v_exp_f32_e32 v56, v56
	v_exp_f32_e32 v57, v57
	v_exp_f32_e32 v58, v58
	v_exp_f32_e32 v59, v59
	v_exp_f32_e32 v60, v60
	v_exp_f32_e32 v61, v61
	v_exp_f32_e32 v62, v62
	v_exp_f32_e32 v63, v63
	v_pk_mul_f32 v[28:29], v[28:29], v[52:53] op_sel_hi:[1,0]
	v_pk_mul_f32 v[26:27], v[26:27], v[52:53] op_sel_hi:[1,0]
	v_cvt_pk_bf16_f32 v72, v56, v57
	v_cvt_pk_bf16_f32 v73, v58, v59
	v_cvt_pk_bf16_f32 v74, v60, v61
	v_cvt_pk_bf16_f32 v75, v62, v63
	v_fma_f32 v64, v64, s91, -v55
	v_fma_f32 v65, v65, s91, -v55
	v_mfma_f32_16x16x32_bf16 v[26:29], v[80:83], v[72:75], v[26:29]
	ds_read_b128 v[80:83], v84 offset:9280
	v_fma_f32 v66, v66, s91, -v55
	v_fma_f32 v67, v67, s91, -v55
	v_fma_f32 v68, v68, s91, -v55
	v_fma_f32 v69, v69, s91, -v55
	v_fma_f32 v70, v70, s91, -v55
	v_fma_f32 v71, v71, s91, -v55
	v_exp_f32_e32 v64, v64
	v_exp_f32_e32 v65, v65
	v_exp_f32_e32 v66, v66
	v_exp_f32_e32 v67, v67
	v_exp_f32_e32 v68, v68
	v_exp_f32_e32 v69, v69
	v_exp_f32_e32 v70, v70
	v_exp_f32_e32 v71, v71
	v_cvt_pk_bf16_f32 v76, v64, v65
	v_cvt_pk_bf16_f32 v77, v66, v67
	v_cvt_pk_bf16_f32 v78, v68, v69
	v_cvt_pk_bf16_f32 v79, v70, v71
	v_pk_mul_f32 v[32:33], v[32:33], v[52:53] op_sel_hi:[1,0]
	v_pk_mul_f32 v[30:31], v[30:31], v[52:53] op_sel_hi:[1,0]
	s_waitcnt lgkmcnt(0)
	v_mfma_f32_16x16x32_bf16 v[26:29], v[80:83], v[76:79], v[26:29]
	v_pk_mul_f32 v[36:37], v[36:37], v[52:53] op_sel_hi:[1,0]
	v_pk_mul_f32 v[34:35], v[34:35], v[52:53] op_sel_hi:[1,0]
	s_waitcnt lgkmcnt(6)
	v_mfma_f32_16x16x32_bf16 v[30:33], v[210:213], v[72:75], v[30:33]
	v_pk_mul_f32 v[40:41], v[40:41], v[52:53] op_sel_hi:[1,0]
	v_pk_mul_f32 v[38:39], v[38:39], v[52:53] op_sel_hi:[1,0]
	s_waitcnt lgkmcnt(5)
	v_mfma_f32_16x16x32_bf16 v[30:33], v[214:217], v[76:79], v[30:33]
	s_waitcnt lgkmcnt(4)
	v_mfma_f32_16x16x32_bf16 v[34:37], v[218:221], v[72:75], v[34:37]
	s_waitcnt lgkmcnt(3)
	v_mfma_f32_16x16x32_bf16 v[34:37], v[222:225], v[76:79], v[34:37]
	s_waitcnt lgkmcnt(2)
	v_mfma_f32_16x16x32_bf16 v[38:41], v[226:229], v[72:75], v[38:41]
	s_waitcnt lgkmcnt(1)
	v_mfma_f32_16x16x32_bf16 v[38:41], v[230:233], v[76:79], v[38:41]
	s_cbranch_vccnz .LBB0_1037
	s_bitcmp1_b32 s12, 0
	s_cselect_b32 s13, 0x4800, 0
	v_add_u32_e32 v72, s13, v46
	s_waitcnt vmcnt(3)
	ds_write_b128 v72, v[14:17]
	s_waitcnt vmcnt(2)
	ds_write_b128 v72, v[10:13] offset:16
	s_waitcnt vmcnt(0)
	ds_write_b128 v72, v[22:25] offset:9216
	ds_write_b128 v72, v[18:21] offset:9232

.LBB0_1045:
	s_add_i32 s68, s12, 1
	s_bitcmp1_b32 s12, 0
	s_cselect_b32 s12, 0x4800, 0
	v_or_b32_e32 v99, s12, v74
	v_add_u32_e32 v93, v99, v81
	ds_read_b128 v[62:65], v93
	ds_read_b128 v[66:69], v93 offset:576
	ds_read_b128 v[70:73], v93 offset:4608
	ds_read_b128 v[88:91], v93 offset:5184
	s_andn2_b64 vcc, exec, s[66:67]
	s_waitcnt vmcnt(1) lgkmcnt(3)
	v_mfma_f32_16x16x32_bf16 v[62:65], v[62:65], v[50:53], 0
	s_waitcnt lgkmcnt(2)
	v_mfma_f32_16x16x32_bf16 v[66:69], v[66:69], v[50:53], 0
	s_nop 5
	v_mul_f32_e32 v59, 0x3e8293ee, v62
	v_mul_f32_e32 v60, 0x3e8293ee, v63
	v_max3_f32 v59, v59, s88, v60
	s_waitcnt lgkmcnt(1)
	v_mfma_f32_16x16x32_bf16 v[70:73], v[70:73], v[50:53], 0
	v_mul_f32_e32 v60, 0x3e8293ee, v64
	s_waitcnt lgkmcnt(0)
	v_mfma_f32_16x16x32_bf16 v[122:125], v[88:91], v[50:53], 0
	v_mul_f32_e32 v88, 0x3e8293ee, v65
	v_max3_f32 v59, v59, v60, v88
	v_mul_f32_e32 v60, 0x3e8293ee, v66
	v_mul_f32_e32 v88, 0x3e8293ee, v67
	v_max3_f32 v59, v59, v60, v88
	v_mul_f32_e32 v60, 0x3e8293ee, v68
	v_mul_f32_e32 v88, 0x3e8293ee, v69
	v_max3_f32 v59, v59, v60, v88
	v_mul_f32_e32 v60, 0x3e8293ee, v70
	v_mul_f32_e32 v88, 0x3e8293ee, v71
	v_max3_f32 v59, v59, v60, v88
	v_mul_f32_e32 v60, 0x3e8293ee, v72
	v_mul_f32_e32 v88, 0x3e8293ee, v73
	v_max3_f32 v59, v59, v60, v88
	v_mul_f32_e32 v60, 0x3e8293ee, v122
	v_mul_f32_e32 v88, 0x3e8293ee, v123
	v_max3_f32 v59, v59, v60, v88
	v_mul_f32_e32 v60, 0x3e8293ee, v124
	v_mul_f32_e32 v88, 0x3e8293ee, v125
	v_max3_f32 v59, v59, v60, v88
	ds_bpermute_b32 v60, v75, v59
	s_waitcnt lgkmcnt(0)
	v_max_f32_e32 v60, v60, v60
	v_max_f32_e32 v59, v59, v60
	ds_bpermute_b32 v60, v1, v59
	s_waitcnt lgkmcnt(0)
	v_max3_f32 v114, v58, v59, v60
	v_fma_f32 v59, v62, s89, -v114
	v_exp_f32_e32 v115, v59
	v_fma_f32 v59, v63, s89, -v114
	v_exp_f32_e32 v116, v59
	v_fma_f32 v59, v64, s89, -v114
	v_exp_f32_e32 v117, v59
	v_fma_f32 v59, v65, s89, -v114
	v_exp_f32_e32 v118, v59
	v_fma_f32 v59, v66, s89, -v114
	v_exp_f32_e32 v119, v59
	v_fma_f32 v59, v67, s89, -v114
	v_exp_f32_e32 v120, v59
	v_fma_f32 v59, v68, s89, -v114
	v_exp_f32_e32 v96, v59
	v_fma_f32 v59, v69, s89, -v114
	v_exp_f32_e32 v110, v59
	v_fma_f32 v59, v70, s89, -v114
	v_exp_f32_e32 v94, v59
	v_fma_f32 v59, v71, s89, -v114
	ds_read_b128 v[62:65], v93 offset:64
	ds_read_b128 v[66:69], v93 offset:640
	v_exp_f32_e32 v108, v59
	v_fma_f32 v59, v72, s89, -v114
	v_exp_f32_e32 v92, v59
	v_fma_f32 v59, v73, s89, -v114
	v_exp_f32_e32 v104, v59
	v_fma_f32 v59, v122, s89, -v114
	v_exp_f32_e32 v90, v59
	v_fma_f32 v59, v123, s89, -v114
	ds_read_b128 v[70:73], v93 offset:4672
	v_exp_f32_e32 v102, v59
	v_fma_f32 v59, v124, s89, -v114
	v_exp_f32_e32 v88, v59
	v_fma_f32 v59, v125, s89, -v114
	ds_read_b128 v[122:125], v93 offset:5248
	s_waitcnt vmcnt(0) lgkmcnt(3)
	v_mfma_f32_16x16x32_bf16 v[62:65], v[62:65], v[54:57], 0
	v_sub_f32_e32 v58, v58, v114
	v_exp_f32_e32 v98, v58
	v_exp_f32_e32 v100, v59
	s_waitcnt lgkmcnt(2)
	v_mfma_f32_16x16x32_bf16 v[66:69], v[66:69], v[54:57], 0
	v_cvt_pk_bf16_f32 v58, v115, v116
	s_nop 1
	v_mul_f32_e32 v89, 0x3e8293ee, v62
	v_mul_f32_e32 v91, 0x3e8293ee, v63
	s_waitcnt lgkmcnt(1)
	v_mfma_f32_16x16x32_bf16 v[70:73], v[70:73], v[54:57], 0
	v_max3_f32 v89, v89, s88, v91
	v_mul_f32_e32 v91, 0x3e8293ee, v64
	v_mul_f32_e32 v93, 0x3e8293ee, v65
	s_waitcnt lgkmcnt(0)
	v_mfma_f32_16x16x32_bf16 v[128:131], v[122:125], v[54:57], 0
	v_max3_f32 v89, v89, v91, v93
	v_mul_f32_e32 v91, 0x3e8293ee, v66
	v_mul_f32_e32 v93, 0x3e8293ee, v67
	v_max3_f32 v89, v89, v91, v93
	v_mul_f32_e32 v91, 0x3e8293ee, v68
	v_mul_f32_e32 v93, 0x3e8293ee, v69
	v_max3_f32 v89, v89, v91, v93
	v_mul_f32_e32 v91, 0x3e8293ee, v70
	v_mul_f32_e32 v93, 0x3e8293ee, v71
	v_max3_f32 v89, v89, v91, v93
	v_mul_f32_e32 v91, 0x3e8293ee, v72
	v_mul_f32_e32 v93, 0x3e8293ee, v73
	v_max3_f32 v89, v89, v91, v93
	v_mul_f32_e32 v91, 0x3e8293ee, v128
	v_mul_f32_e32 v93, 0x3e8293ee, v129
	v_max3_f32 v89, v89, v91, v93
	v_mul_f32_e32 v91, 0x3e8293ee, v130
	v_mul_f32_e32 v93, 0x3e8293ee, v131
	v_max3_f32 v89, v89, v91, v93
	ds_bpermute_b32 v91, v75, v89
	v_pk_mul_f32 v[4:5], v[4:5], v[98:99] op_sel_hi:[1,0]
	v_pk_mul_f32 v[2:3], v[2:3], v[98:99] op_sel_hi:[1,0]
	v_pk_mul_f32 v[12:13], v[12:13], v[98:99] op_sel_hi:[1,0]
	v_pk_mul_f32 v[10:11], v[10:11], v[98:99] op_sel_hi:[1,0]
	s_waitcnt lgkmcnt(0)
	v_max_f32_e32 v91, v91, v91
	v_max_f32_e32 v89, v89, v91
	ds_bpermute_b32 v91, v1, v89
	v_pk_mul_f32 v[16:17], v[16:17], v[98:99] op_sel_hi:[1,0]
	v_pk_mul_f32 v[14:15], v[14:15], v[98:99] op_sel_hi:[1,0]
	v_cvt_pk_bf16_f32 v59, v117, v118
	v_cvt_pk_bf16_f32 v60, v119, v120
	s_waitcnt lgkmcnt(0)
	v_max3_f32 v121, v61, v89, v91
	v_fma_f32 v62, v62, s89, -v121
	v_exp_f32_e32 v122, v62
	v_fma_f32 v62, v63, s89, -v121
	v_exp_f32_e32 v123, v62
	v_fma_f32 v62, v64, s89, -v121
	v_exp_f32_e32 v124, v62
	v_fma_f32 v62, v65, s89, -v121
	v_exp_f32_e32 v125, v62
	v_fma_f32 v62, v66, s89, -v121
	v_exp_f32_e32 v126, v62
	v_fma_f32 v62, v67, s89, -v121
	v_exp_f32_e32 v127, v62
	v_fma_f32 v62, v68, s89, -v121
	v_exp_f32_e32 v97, v62
	v_fma_f32 v62, v69, s89, -v121
	v_exp_f32_e32 v111, v62
	v_fma_f32 v62, v70, s89, -v121
	v_exp_f32_e32 v95, v62
	v_fma_f32 v62, v71, s89, -v121
	v_exp_f32_e32 v109, v62
	v_fma_f32 v62, v72, s89, -v121
	v_exp_f32_e32 v93, v62
	v_fma_f32 v62, v73, s89, -v121
	v_exp_f32_e32 v105, v62
	v_fma_f32 v62, v128, s89, -v121
	v_exp_f32_e32 v91, v62
	v_fma_f32 v62, v129, s89, -v121
	v_exp_f32_e32 v103, v62
	v_fma_f32 v62, v130, s89, -v121
	v_exp_f32_e32 v89, v62
	v_fma_f32 v62, v131, s89, -v121
	v_exp_f32_e32 v101, v62
	v_pk_mul_f32 v[64:65], v[20:21], v[98:99] op_sel_hi:[1,0]
	v_pk_mul_f32 v[62:63], v[18:19], v[98:99] op_sel_hi:[1,0]
	v_add_u32_e32 v99, v99, v87
	ds_read_b128 v[210:213], v99 offset:9280
	ds_read_b128 v[214:217], v99 offset:11520
	ds_read_b128 v[218:221], v99 offset:11584
	ds_read_b128 v[222:225], v99 offset:13824
	ds_read_b128 v[226:229], v99 offset:13888
	ds_read_b128 v[230:233], v99 offset:16128
	ds_read_b128 v[234:237], v99 offset:16192
	ds_read_b128 v[128:131], v99 offset:9216
	v_sub_f32_e32 v61, v61, v121
	v_exp_f32_e32 v112, v61
	v_cvt_pk_bf16_f32 v61, v96, v110
	v_cvt_pk_bf16_f32 v70, v122, v123
	v_cvt_pk_bf16_f32 v71, v124, v125
	v_pk_mul_f32 v[8:9], v[8:9], v[112:113] op_sel_hi:[1,0]
	v_pk_mul_f32 v[6:7], v[6:7], v[112:113] op_sel_hi:[1,0]
	v_cvt_pk_bf16_f32 v72, v126, v127
	v_cvt_pk_bf16_f32 v73, v97, v111
	s_waitcnt lgkmcnt(0)
	v_mfma_f32_16x16x32_bf16 v[2:5], v[128:131], v[58:61], v[2:5]
	v_cvt_pk_bf16_f32 v18, v94, v108
	v_cvt_pk_bf16_f32 v19, v92, v104
	v_cvt_pk_bf16_f32 v20, v90, v102
	v_mfma_f32_16x16x32_bf16 v[6:9], v[128:131], v[70:73], v[6:9]
	v_cvt_pk_bf16_f32 v21, v88, v100
	v_pk_mul_f32 v[68:69], v[32:33], v[112:113] op_sel_hi:[1,0]
	v_pk_mul_f32 v[66:67], v[30:31], v[112:113] op_sel_hi:[1,0]
	v_cvt_pk_bf16_f32 v30, v95, v109
	v_cvt_pk_bf16_f32 v31, v93, v105
	v_cvt_pk_bf16_f32 v32, v91, v103
	v_cvt_pk_bf16_f32 v33, v89, v101
	s_waitcnt lgkmcnt(7)
	v_mfma_f32_16x16x32_bf16 v[2:5], v[210:213], v[18:21], v[2:5]
	v_mul_f32_e64 v24, v24, v112
	v_mul_f32_e64 v25, v25, v112
	v_pk_mul_f32 v[22:23], v[22:23], v[112:113] op_sel_hi:[1,0]
	v_pk_mul_f32 v[28:29], v[28:29], v[112:113] op_sel_hi:[1,0]
	v_mfma_f32_16x16x32_bf16 v[6:9], v[210:213], v[30:33], v[6:9]
	v_pk_mul_f32 v[26:27], v[26:27], v[112:113] op_sel_hi:[1,0]
	s_waitcnt lgkmcnt(6)
	v_mfma_f32_16x16x32_bf16 v[10:13], v[214:217], v[58:61], v[10:13]
	v_mfma_f32_16x16x32_bf16 v[22:25], v[214:217], v[70:73], v[22:25]
	s_waitcnt lgkmcnt(5)
	v_mfma_f32_16x16x32_bf16 v[10:13], v[218:221], v[18:21], v[10:13]
	v_mfma_f32_16x16x32_bf16 v[22:25], v[218:221], v[30:33], v[22:25]
	s_waitcnt lgkmcnt(4)
	v_mfma_f32_16x16x32_bf16 v[14:17], v[222:225], v[58:61], v[14:17]
	v_mfma_f32_16x16x32_bf16 v[26:29], v[222:225], v[70:73], v[26:29]
	s_waitcnt lgkmcnt(3)
	v_mfma_f32_16x16x32_bf16 v[14:17], v[226:229], v[18:21], v[14:17]
	v_mfma_f32_16x16x32_bf16 v[26:29], v[226:229], v[30:33], v[26:29]
	s_waitcnt lgkmcnt(2)
	v_mfma_f32_16x16x32_bf16 v[58:61], v[230:233], v[58:61], v[62:65]
	v_mfma_f32_16x16x32_bf16 v[62:65], v[230:233], v[70:73], v[66:69]
	s_nop 2
	s_waitcnt lgkmcnt(1)
	v_mfma_f32_16x16x32_bf16 v[18:21], v[234:237], v[18:21], v[58:61]
	v_mfma_f32_16x16x32_bf16 v[30:33], v[234:237], v[30:33], v[62:65]
	s_cbranch_vccnz .LBB0_1042
	s_bitcmp1_b32 s68, 0
	s_cselect_b32 s12, 0x4800, 0
	v_add_u32_e32 v58, s12, v80
	ds_write_b128 v58, v[34:37]
	ds_write_b128 v58, v[38:41] offset:16
	ds_write_b128 v58, v[42:45] offset:9216
	ds_write_b128 v58, v[46:49] offset:9232
	s_branch .LBB0_1042

.LBB0_1056:
	s_cmp_gt_u32 s14, 3
	s_cselect_b64 s[68:69], -1, 0
	s_bitcmp1_b32 s14, 0
	s_cselect_b32 s14, 0x4800, 0
	v_or_b32_e32 v87, s14, v58
	v_add_u32_e32 v61, v87, v56
	ds_read_b128 v[62:65], v61
	ds_read_b128 v[66:69], v61 offset:64
	v_add_u32_e32 v87, v87, v57
	ds_read_b128 v[88:91], v87 offset:9216
	s_waitcnt vmcnt(1) lgkmcnt(2)
	v_mfma_f32_16x16x32_bf16 v[62:65], v[62:65], v[2:5], 0
	ds_read_b128 v[70:73], v61 offset:640
	ds_read_b128 v[74:77], v61 offset:4672
	ds_read_b128 v[78:81], v61 offset:5248
	s_waitcnt vmcnt(0) lgkmcnt(4)
	v_mfma_f32_16x16x32_bf16 v[62:65], v[66:69], v[6:9], v[62:65]
	ds_read_b128 v[66:69], v61 offset:576
	s_waitcnt lgkmcnt(0)
	v_mfma_f32_16x16x32_bf16 v[66:69], v[66:69], v[2:5], 0
	s_nop 4
	v_mul_f32_e32 v62, 0x3e38aa3b, v62
	v_mul_f32_e32 v63, 0x3e38aa3b, v63
	v_mul_f32_e32 v64, 0x3e38aa3b, v64
	v_mfma_f32_16x16x32_bf16 v[66:69], v[70:73], v[6:9], v[66:69]
	ds_read_b128 v[70:73], v61 offset:4608
	v_mul_f32_e32 v65, 0x3e38aa3b, v65
	s_waitcnt lgkmcnt(0)
	v_mfma_f32_16x16x32_bf16 v[70:73], v[70:73], v[2:5], 0
	s_nop 3
	v_mul_f32_e32 v66, 0x3e38aa3b, v66
	v_mul_f32_e32 v67, 0x3e38aa3b, v67
	v_mul_f32_e32 v68, 0x3e38aa3b, v68
	v_mfma_f32_16x16x32_bf16 v[70:73], v[74:77], v[6:9], v[70:73]
	ds_read_b128 v[74:77], v61 offset:5184
	v_add_u32_e32 v61, s12, v59
	v_mul_f32_e32 v69, 0x3e38aa3b, v69
	s_waitcnt lgkmcnt(0)
	v_mfma_f32_16x16x32_bf16 v[74:77], v[74:77], v[2:5], 0
	s_nop 2
	v_mul_f32_e32 v70, 0x3e38aa3b, v70
	v_mul_f32_e32 v71, 0x3e38aa3b, v71
	v_mul_f32_e32 v72, 0x3e38aa3b, v72
	v_mfma_f32_16x16x32_bf16 v[74:77], v[78:81], v[6:9], v[74:77]
	v_add_u32_e32 v78, 0xfffffe3f, v61
	v_cmp_gt_u32_e32 vcc, s36, v78
	s_and_b64 vcc, s[68:69], vcc
	v_add_u32_e32 v78, 0xfffffe40, v61
	v_cndmask_b32_e32 v62, v62, v150, vcc
	v_cmp_gt_u32_e32 vcc, s36, v78
	s_and_b64 vcc, s[68:69], vcc
	v_add_u32_e32 v79, 0xfffffe41, v61
	v_cndmask_b32_e32 v63, v63, v150, vcc
	v_cmp_gt_u32_e32 vcc, s36, v79
	s_and_b64 vcc, s[68:69], vcc
	v_add_u32_e32 v79, 0xfffffe42, v61
	v_cndmask_b32_e32 v64, v64, v150, vcc
	v_cmp_gt_u32_e32 vcc, s36, v79
	s_and_b64 vcc, s[68:69], vcc
	v_add_u32_e32 v79, 0xfffffe43, v61
	v_cndmask_b32_e32 v65, v65, v150, vcc
	v_cmp_gt_u32_e32 vcc, s36, v79
	s_and_b64 vcc, s[68:69], vcc
	v_add_u32_e32 v79, 0xfffffe44, v61
	v_cndmask_b32_e32 v66, v66, v150, vcc
	v_cmp_gt_u32_e32 vcc, s36, v79
	s_and_b64 vcc, s[68:69], vcc
	v_add_u32_e32 v79, 0xfffffe45, v61
	v_cndmask_b32_e32 v67, v67, v150, vcc
	v_cmp_gt_u32_e32 vcc, s36, v79
	s_and_b64 vcc, s[68:69], vcc
	v_add_u32_e32 v79, 0xfffffe46, v61
	v_cndmask_b32_e32 v68, v68, v150, vcc
	v_cmp_gt_u32_e32 vcc, s36, v79
	s_and_b64 vcc, s[68:69], vcc
	v_add_u32_e32 v79, 0xfffffe5f, v61
	v_cndmask_b32_e32 v69, v69, v150, vcc
	v_cmp_gt_u32_e32 vcc, s36, v79
	s_and_b64 vcc, s[68:69], vcc
	v_add_u32_e32 v79, 0xfffffe60, v61
	v_cndmask_b32_e32 v70, v70, v150, vcc
	v_cmp_gt_u32_e32 vcc, s36, v79
	s_and_b64 vcc, s[68:69], vcc
	v_add_u32_e32 v79, 0xfffffe61, v61
	v_cndmask_b32_e32 v71, v71, v150, vcc
	v_cmp_gt_u32_e32 vcc, s36, v79
	s_and_b64 vcc, s[68:69], vcc
	v_add_u32_e32 v79, 0xfffffe62, v61
	v_cndmask_b32_e32 v72, v72, v150, vcc
	v_cmp_gt_u32_e32 vcc, s36, v79
	v_mul_f32_e32 v73, 0x3e38aa3b, v73
	s_and_b64 vcc, s[68:69], vcc
	v_add_u32_e32 v79, 0xfffffe63, v61
	v_cndmask_b32_e32 v73, v73, v150, vcc
	v_cmp_gt_u32_e32 vcc, s36, v79
	v_mul_f32_e32 v74, 0x3e38aa3b, v74
	s_and_b64 vcc, s[68:69], vcc
	v_add_u32_e32 v79, 0xfffffe64, v61
	v_max3_f32 v78, v62, s88, v63
	v_cndmask_b32_e32 v74, v74, v150, vcc
	v_cmp_gt_u32_e32 vcc, s36, v79
	v_max3_f32 v78, v78, v64, v65
	v_mul_f32_e32 v75, 0x3e38aa3b, v75
	s_and_b64 vcc, s[68:69], vcc
	v_add_u32_e32 v79, 0xfffffe65, v61
	v_max3_f32 v78, v78, v66, v67
	v_cndmask_b32_e32 v75, v75, v150, vcc
	v_cmp_gt_u32_e32 vcc, s36, v79
	v_max3_f32 v78, v78, v68, v69
	v_mul_f32_e32 v76, 0x3e38aa3b, v76
	s_and_b64 vcc, s[68:69], vcc
	v_add_u32_e32 v61, 0xfffffe66, v61
	v_max3_f32 v78, v78, v70, v71
	v_cndmask_b32_e32 v76, v76, v150, vcc
	v_cmp_gt_u32_e32 vcc, s36, v61
	v_max3_f32 v78, v78, v72, v73
	v_mul_f32_e32 v77, 0x3e38aa3b, v77
	s_and_b64 vcc, s[68:69], vcc
	v_max3_f32 v78, v78, v74, v75
	v_cndmask_b32_e32 v77, v77, v150, vcc
	v_max3_f32 v61, v78, v76, v77
	ds_bpermute_b32 v78, v45, v61
	s_andn2_b64 vcc, exec, s[66:67]
	s_waitcnt lgkmcnt(0)
	v_max_f32_e32 v78, v78, v78
	v_max_f32_e32 v61, v61, v78
	ds_bpermute_b32 v78, v55, v61
	s_waitcnt lgkmcnt(0)
	ds_read_b128 v[210:213], v87 offset:11520
	ds_read_b128 v[214:217], v87 offset:11584
	ds_read_b128 v[218:221], v87 offset:13824
	ds_read_b128 v[222:225], v87 offset:13888
	ds_read_b128 v[226:229], v87 offset:16128
	ds_read_b128 v[230:233], v87 offset:16192
	v_max3_f32 v61, v52, v61, v78
	v_sub_f32_e32 v52, v52, v61
	v_sub_f32_e32 v62, v62, v61
	v_sub_f32_e32 v63, v63, v61
	v_sub_f32_e32 v64, v64, v61
	v_sub_f32_e32 v65, v65, v61
	v_sub_f32_e32 v66, v66, v61
	v_sub_f32_e32 v67, v67, v61
	v_sub_f32_e32 v68, v68, v61
	v_sub_f32_e32 v69, v69, v61
	v_exp_f32_e32 v52, v52
	v_exp_f32_e32 v62, v62
	v_exp_f32_e32 v63, v63
	v_exp_f32_e32 v64, v64
	v_exp_f32_e32 v65, v65
	v_exp_f32_e32 v66, v66
	v_exp_f32_e32 v67, v67
	v_exp_f32_e32 v68, v68
	v_exp_f32_e32 v69, v69
	v_pk_mul_f32 v[28:29], v[28:29], v[52:53] op_sel_hi:[1,0]
	v_pk_mul_f32 v[26:27], v[26:27], v[52:53] op_sel_hi:[1,0]
	v_cvt_pk_bf16_f32 v78, v62, v63
	v_cvt_pk_bf16_f32 v79, v64, v65
	v_cvt_pk_bf16_f32 v80, v66, v67
	v_cvt_pk_bf16_f32 v81, v68, v69
	v_sub_f32_e32 v70, v70, v61
	v_sub_f32_e32 v71, v71, v61
	v_mfma_f32_16x16x32_bf16 v[26:29], v[88:91], v[78:81], v[26:29]
	ds_read_b128 v[88:91], v87 offset:9280
	v_sub_f32_e32 v72, v72, v61
	v_sub_f32_e32 v73, v73, v61
	v_sub_f32_e32 v74, v74, v61
	v_sub_f32_e32 v75, v75, v61
	v_sub_f32_e32 v76, v76, v61
	v_sub_f32_e32 v77, v77, v61
	v_exp_f32_e32 v70, v70
	v_exp_f32_e32 v71, v71
	v_exp_f32_e32 v72, v72
	v_exp_f32_e32 v73, v73
	v_exp_f32_e32 v74, v74
	v_exp_f32_e32 v75, v75
	v_exp_f32_e32 v76, v76
	v_exp_f32_e32 v77, v77
	v_cvt_pk_bf16_f32 v82, v70, v71
	v_cvt_pk_bf16_f32 v83, v72, v73
	v_cvt_pk_bf16_f32 v84, v74, v75
	v_cvt_pk_bf16_f32 v85, v76, v77
	v_pk_mul_f32 v[32:33], v[32:33], v[52:53] op_sel_hi:[1,0]
	v_pk_mul_f32 v[30:31], v[30:31], v[52:53] op_sel_hi:[1,0]
	s_waitcnt lgkmcnt(0)
	v_mfma_f32_16x16x32_bf16 v[26:29], v[88:91], v[82:85], v[26:29]
	v_pk_mul_f32 v[36:37], v[36:37], v[52:53] op_sel_hi:[1,0]
	v_pk_mul_f32 v[34:35], v[34:35], v[52:53] op_sel_hi:[1,0]
	s_waitcnt lgkmcnt(6)
	v_mfma_f32_16x16x32_bf16 v[30:33], v[210:213], v[78:81], v[30:33]
	v_pk_mul_f32 v[40:41], v[40:41], v[52:53] op_sel_hi:[1,0]
	v_pk_mul_f32 v[38:39], v[38:39], v[52:53] op_sel_hi:[1,0]
	s_waitcnt lgkmcnt(5)
	v_mfma_f32_16x16x32_bf16 v[30:33], v[214:217], v[82:85], v[30:33]
	s_waitcnt lgkmcnt(4)
	v_mfma_f32_16x16x32_bf16 v[34:37], v[218:221], v[78:81], v[34:37]
	s_waitcnt lgkmcnt(3)
	v_mfma_f32_16x16x32_bf16 v[34:37], v[222:225], v[82:85], v[34:37]
	s_waitcnt lgkmcnt(2)
	v_mfma_f32_16x16x32_bf16 v[38:41], v[226:229], v[78:81], v[38:41]
	s_waitcnt lgkmcnt(1)
	v_mfma_f32_16x16x32_bf16 v[38:41], v[230:233], v[82:85], v[38:41]
	s_cbranch_vccnz .LBB0_1058
	s_bitcmp1_b32 s13, 0
	s_cselect_b32 s14, 0x4800, 0
	v_add_u32_e32 v78, s14, v48
	ds_write_b128 v78, v[14:17]
	ds_write_b128 v78, v[10:13] offset:16
	ds_write_b128 v78, v[22:25] offset:9216
	ds_write_b128 v78, v[18:21] offset:9232

.LBB0_1076:
	s_bitcmp1_b32 s12, 0
	s_cselect_b32 s12, 0x4800, 0
	v_or_b32_e32 v99, s12, v74
	v_add_u32_e32 v93, v99, v77
	ds_read_b128 v[62:65], v93
	ds_read_b128 v[66:69], v93 offset:576
	ds_read_b128 v[70:73], v93 offset:4608
	ds_read_b128 v[88:91], v93 offset:5184
	s_andn2_b64 vcc, exec, s[66:67]
	s_waitcnt vmcnt(1) lgkmcnt(3)
	v_mfma_f32_16x16x32_bf16 v[62:65], v[62:65], v[42:45], 0
	s_waitcnt lgkmcnt(2)
	v_mfma_f32_16x16x32_bf16 v[66:69], v[66:69], v[42:45], 0
	s_nop 5
	v_mul_f32_e32 v59, 0x3e8293ee, v62
	v_mul_f32_e32 v60, 0x3e8293ee, v63
	v_max3_f32 v59, v59, s88, v60
	s_waitcnt lgkmcnt(1)
	v_mfma_f32_16x16x32_bf16 v[70:73], v[70:73], v[42:45], 0
	v_mul_f32_e32 v60, 0x3e8293ee, v64
	v_mul_f32_e32 v81, 0x3e8293ee, v65
	v_max3_f32 v59, v59, v60, v81
	s_waitcnt lgkmcnt(0)
	v_mfma_f32_16x16x32_bf16 v[122:125], v[88:91], v[42:45], 0
	v_mul_f32_e32 v60, 0x3e8293ee, v66
	v_mul_f32_e32 v81, 0x3e8293ee, v67
	v_max3_f32 v59, v59, v60, v81
	v_mul_f32_e32 v60, 0x3e8293ee, v68
	v_mul_f32_e32 v81, 0x3e8293ee, v69
	v_max3_f32 v59, v59, v60, v81
	v_mul_f32_e32 v60, 0x3e8293ee, v70
	v_mul_f32_e32 v81, 0x3e8293ee, v71
	v_max3_f32 v59, v59, v60, v81
	v_mul_f32_e32 v60, 0x3e8293ee, v72
	v_mul_f32_e32 v81, 0x3e8293ee, v73
	v_max3_f32 v59, v59, v60, v81
	v_mul_f32_e32 v60, 0x3e8293ee, v122
	v_mul_f32_e32 v81, 0x3e8293ee, v123
	v_max3_f32 v59, v59, v60, v81
	v_mul_f32_e32 v60, 0x3e8293ee, v124
	v_mul_f32_e32 v81, 0x3e8293ee, v125
	v_max3_f32 v59, v59, v60, v81
	ds_bpermute_b32 v60, v114, v59
	s_waitcnt lgkmcnt(0)
	v_max_f32_e32 v60, v60, v60
	v_max_f32_e32 v59, v59, v60
	ds_bpermute_b32 v60, v75, v59
	s_waitcnt lgkmcnt(0)
	v_max3_f32 v81, v58, v59, v60
	v_fma_f32 v59, v62, s89, -v81
	v_exp_f32_e32 v115, v59
	v_fma_f32 v59, v63, s89, -v81
	v_exp_f32_e32 v116, v59
	v_fma_f32 v59, v64, s89, -v81
	v_exp_f32_e32 v117, v59
	v_fma_f32 v59, v65, s89, -v81
	v_exp_f32_e32 v118, v59
	v_fma_f32 v59, v66, s89, -v81
	v_exp_f32_e32 v119, v59
	v_fma_f32 v59, v67, s89, -v81
	v_exp_f32_e32 v120, v59
	v_fma_f32 v59, v68, s89, -v81
	v_exp_f32_e32 v96, v59
	v_fma_f32 v59, v69, s89, -v81
	v_exp_f32_e32 v110, v59
	v_fma_f32 v59, v70, s89, -v81
	v_exp_f32_e32 v94, v59
	v_fma_f32 v59, v71, s89, -v81
	ds_read_b128 v[62:65], v93 offset:64
	ds_read_b128 v[66:69], v93 offset:640
	v_exp_f32_e32 v108, v59
	v_fma_f32 v59, v72, s89, -v81
	v_exp_f32_e32 v92, v59
	v_fma_f32 v59, v73, s89, -v81
	v_exp_f32_e32 v104, v59
	v_fma_f32 v59, v122, s89, -v81
	v_exp_f32_e32 v90, v59
	v_fma_f32 v59, v123, s89, -v81
	ds_read_b128 v[70:73], v93 offset:4672
	v_exp_f32_e32 v102, v59
	v_fma_f32 v59, v124, s89, -v81
	v_exp_f32_e32 v88, v59
	v_fma_f32 v59, v125, s89, -v81
	ds_read_b128 v[122:125], v93 offset:5248
	s_waitcnt vmcnt(0) lgkmcnt(3)
	v_mfma_f32_16x16x32_bf16 v[62:65], v[62:65], v[46:49], 0
	v_sub_f32_e32 v58, v58, v81
	v_exp_f32_e32 v98, v58
	v_exp_f32_e32 v100, v59
	s_waitcnt lgkmcnt(2)
	v_mfma_f32_16x16x32_bf16 v[66:69], v[66:69], v[46:49], 0
	v_cvt_pk_bf16_f32 v58, v115, v116
	s_nop 1
	v_mul_f32_e32 v89, 0x3e8293ee, v62
	v_mul_f32_e32 v91, 0x3e8293ee, v63
	s_waitcnt lgkmcnt(1)
	v_mfma_f32_16x16x32_bf16 v[70:73], v[70:73], v[46:49], 0
	v_max3_f32 v89, v89, s88, v91
	v_mul_f32_e32 v91, 0x3e8293ee, v64
	v_mul_f32_e32 v93, 0x3e8293ee, v65
	s_waitcnt lgkmcnt(0)
	v_mfma_f32_16x16x32_bf16 v[128:131], v[122:125], v[46:49], 0
	v_max3_f32 v89, v89, v91, v93
	v_mul_f32_e32 v91, 0x3e8293ee, v66
	v_mul_f32_e32 v93, 0x3e8293ee, v67
	v_max3_f32 v89, v89, v91, v93
	v_mul_f32_e32 v91, 0x3e8293ee, v68
	v_mul_f32_e32 v93, 0x3e8293ee, v69
	v_max3_f32 v89, v89, v91, v93
	v_mul_f32_e32 v91, 0x3e8293ee, v70
	v_mul_f32_e32 v93, 0x3e8293ee, v71
	v_max3_f32 v89, v89, v91, v93
	v_mul_f32_e32 v91, 0x3e8293ee, v72
	v_mul_f32_e32 v93, 0x3e8293ee, v73
	v_max3_f32 v89, v89, v91, v93
	v_mul_f32_e32 v91, 0x3e8293ee, v128
	v_mul_f32_e32 v93, 0x3e8293ee, v129
	v_max3_f32 v89, v89, v91, v93
	v_mul_f32_e32 v91, 0x3e8293ee, v130
	v_mul_f32_e32 v93, 0x3e8293ee, v131
	v_max3_f32 v89, v89, v91, v93
	ds_bpermute_b32 v91, v114, v89
	v_pk_mul_f32 v[8:9], v[8:9], v[98:99] op_sel_hi:[1,0]
	v_pk_mul_f32 v[6:7], v[6:7], v[98:99] op_sel_hi:[1,0]
	v_pk_mul_f32 v[12:13], v[12:13], v[98:99] op_sel_hi:[1,0]
	v_pk_mul_f32 v[10:11], v[10:11], v[98:99] op_sel_hi:[1,0]
	s_waitcnt lgkmcnt(0)
	v_max_f32_e32 v91, v91, v91
	v_max_f32_e32 v89, v89, v91
	ds_bpermute_b32 v91, v75, v89
	v_pk_mul_f32 v[20:21], v[20:21], v[98:99] op_sel_hi:[1,0]
	v_pk_mul_f32 v[18:19], v[18:19], v[98:99] op_sel_hi:[1,0]
	v_cvt_pk_bf16_f32 v59, v117, v118
	v_cvt_pk_bf16_f32 v60, v119, v120
	s_waitcnt lgkmcnt(0)
	v_max3_f32 v121, v61, v89, v91
	v_fma_f32 v62, v62, s89, -v121
	v_exp_f32_e32 v122, v62
	v_fma_f32 v62, v63, s89, -v121
	v_exp_f32_e32 v123, v62
	v_fma_f32 v62, v64, s89, -v121
	v_exp_f32_e32 v124, v62
	v_fma_f32 v62, v65, s89, -v121
	v_exp_f32_e32 v125, v62
	v_fma_f32 v62, v66, s89, -v121
	v_exp_f32_e32 v126, v62
	v_fma_f32 v62, v67, s89, -v121
	v_exp_f32_e32 v127, v62
	v_fma_f32 v62, v68, s89, -v121
	v_exp_f32_e32 v97, v62
	v_fma_f32 v62, v69, s89, -v121
	v_exp_f32_e32 v111, v62
	v_fma_f32 v62, v70, s89, -v121
	v_exp_f32_e32 v95, v62
	v_fma_f32 v62, v71, s89, -v121
	v_exp_f32_e32 v109, v62
	v_fma_f32 v62, v72, s89, -v121
	v_exp_f32_e32 v93, v62
	v_fma_f32 v62, v73, s89, -v121
	v_exp_f32_e32 v105, v62
	v_fma_f32 v62, v128, s89, -v121
	v_exp_f32_e32 v91, v62
	v_fma_f32 v62, v129, s89, -v121
	v_exp_f32_e32 v103, v62
	v_fma_f32 v62, v130, s89, -v121
	v_exp_f32_e32 v89, v62
	v_fma_f32 v62, v131, s89, -v121
	v_exp_f32_e32 v101, v62
	v_pk_mul_f32 v[64:65], v[24:25], v[98:99] op_sel_hi:[1,0]
	v_pk_mul_f32 v[62:63], v[22:23], v[98:99] op_sel_hi:[1,0]
	v_add_u32_e32 v99, v99, v87
	ds_read_b128 v[210:213], v99 offset:9280
	ds_read_b128 v[214:217], v99 offset:11520
	ds_read_b128 v[218:221], v99 offset:11584
	ds_read_b128 v[222:225], v99 offset:13824
	ds_read_b128 v[226:229], v99 offset:13888
	ds_read_b128 v[230:233], v99 offset:16128
	ds_read_b128 v[234:237], v99 offset:16192
	ds_read_b128 v[128:131], v99 offset:9216
	v_sub_f32_e32 v61, v61, v121
	v_exp_f32_e32 v112, v61
	v_cvt_pk_bf16_f32 v61, v96, v110
	v_cvt_pk_bf16_f32 v70, v122, v123
	v_cvt_pk_bf16_f32 v71, v124, v125
	v_pk_mul_f32 v[4:5], v[4:5], v[112:113] op_sel_hi:[1,0]
	v_pk_mul_f32 v[2:3], v[2:3], v[112:113] op_sel_hi:[1,0]
	v_cvt_pk_bf16_f32 v72, v126, v127
	v_cvt_pk_bf16_f32 v73, v97, v111
	s_waitcnt lgkmcnt(0)
	v_mfma_f32_16x16x32_bf16 v[6:9], v[128:131], v[58:61], v[6:9]
	v_cvt_pk_bf16_f32 v22, v94, v108
	v_cvt_pk_bf16_f32 v23, v92, v104
	v_cvt_pk_bf16_f32 v24, v90, v102
	v_mfma_f32_16x16x32_bf16 v[2:5], v[128:131], v[70:73], v[2:5]
	v_cvt_pk_bf16_f32 v25, v88, v100
	v_pk_mul_f32 v[68:69], v[32:33], v[112:113] op_sel_hi:[1,0]
	v_pk_mul_f32 v[66:67], v[30:31], v[112:113] op_sel_hi:[1,0]
	v_cvt_pk_bf16_f32 v30, v95, v109
	v_cvt_pk_bf16_f32 v31, v93, v105
	v_cvt_pk_bf16_f32 v32, v91, v103
	v_cvt_pk_bf16_f32 v33, v89, v101
	s_waitcnt lgkmcnt(7)
	v_mfma_f32_16x16x32_bf16 v[6:9], v[210:213], v[22:25], v[6:9]
	v_mul_f32_e64 v16, v16, v112
	v_mul_f32_e64 v17, v17, v112
	v_pk_mul_f32 v[14:15], v[14:15], v[112:113] op_sel_hi:[1,0]
	v_pk_mul_f32 v[28:29], v[28:29], v[112:113] op_sel_hi:[1,0]
	v_mfma_f32_16x16x32_bf16 v[2:5], v[210:213], v[30:33], v[2:5]
	v_pk_mul_f32 v[26:27], v[26:27], v[112:113] op_sel_hi:[1,0]
	s_waitcnt lgkmcnt(6)
	v_mfma_f32_16x16x32_bf16 v[10:13], v[214:217], v[58:61], v[10:13]
	v_mfma_f32_16x16x32_bf16 v[14:17], v[214:217], v[70:73], v[14:17]
	s_waitcnt lgkmcnt(5)
	v_mfma_f32_16x16x32_bf16 v[10:13], v[218:221], v[22:25], v[10:13]
	v_mfma_f32_16x16x32_bf16 v[14:17], v[218:221], v[30:33], v[14:17]
	s_waitcnt lgkmcnt(4)
	v_mfma_f32_16x16x32_bf16 v[18:21], v[222:225], v[58:61], v[18:21]
	v_mfma_f32_16x16x32_bf16 v[26:29], v[222:225], v[70:73], v[26:29]
	s_waitcnt lgkmcnt(3)
	v_mfma_f32_16x16x32_bf16 v[18:21], v[226:229], v[22:25], v[18:21]
	v_mfma_f32_16x16x32_bf16 v[26:29], v[226:229], v[30:33], v[26:29]
	s_waitcnt lgkmcnt(2)
	v_mfma_f32_16x16x32_bf16 v[58:61], v[230:233], v[58:61], v[62:65]
	v_mfma_f32_16x16x32_bf16 v[62:65], v[230:233], v[70:73], v[66:69]
	s_nop 2
	s_waitcnt lgkmcnt(1)
	v_mfma_f32_16x16x32_bf16 v[22:25], v[234:237], v[22:25], v[58:61]
	v_mfma_f32_16x16x32_bf16 v[30:33], v[234:237], v[30:33], v[62:65]
	s_cbranch_vccnz .LBB0_1073
	s_bitcmp1_b32 s68, 0
	s_cselect_b32 s12, 0x4800, 0
	v_add_u32_e32 v58, s12, v80
	ds_write_b128 v58, v[38:41]
	ds_write_b128 v58, v[34:37] offset:16
	ds_write_b128 v58, v[50:53] offset:9216
	ds_write_b128 v58, v[54:57] offset:9232
	s_branch .LBB0_1073

.LBB0_1163:
	s_add_i32 s12, s13, 1
	s_bitcmp1_b32 s13, 0
	s_cselect_b32 s13, 0x4800, 0
	v_or_b32_e32 v80, s13, v42
	v_add_u32_e32 v55, v80, v47
	ds_read_b128 v[56:59], v55
	ds_read_b128 v[60:63], v55 offset:64
	v_add_u32_e32 v84, v80, v53
	ds_read_b128 v[80:83], v84 offset:9216
	s_andn2_b64 vcc, exec, s[60:61]
	s_waitcnt lgkmcnt(2)
	v_mfma_f32_16x16x32_bf16 v[56:59], v[56:59], v[2:5], 0
	ds_read_b128 v[64:67], v55 offset:640
	ds_read_b128 v[68:71], v55 offset:4672
	ds_read_b128 v[72:75], v55 offset:5248
	s_waitcnt lgkmcnt(4)
	v_mfma_f32_16x16x32_bf16 v[56:59], v[60:63], v[6:9], v[56:59]
	ds_read_b128 v[60:63], v55 offset:576
	s_waitcnt lgkmcnt(0)
	v_mfma_f32_16x16x32_bf16 v[60:63], v[60:63], v[2:5], 0
	v_mfma_f32_16x16x32_bf16 v[60:63], v[64:67], v[6:9], v[60:63]
	ds_read_b128 v[64:67], v55 offset:4608
	s_waitcnt lgkmcnt(0)
	v_mfma_f32_16x16x32_bf16 v[64:67], v[64:67], v[2:5], 0
	v_mfma_f32_16x16x32_bf16 v[64:67], v[68:71], v[6:9], v[64:67]
	ds_read_b128 v[68:71], v55 offset:5184
	ds_read_b128 v[210:213], v84 offset:11520
	ds_read_b128 v[214:217], v84 offset:11584
	ds_read_b128 v[218:221], v84 offset:13824
	ds_read_b128 v[222:225], v84 offset:13888
	ds_read_b128 v[226:229], v84 offset:16128
	ds_read_b128 v[230:233], v84 offset:16192
	v_mul_f32_e32 v55, 0x3e38aa3b, v56
	s_waitcnt lgkmcnt(0)
	v_mfma_f32_16x16x32_bf16 v[68:71], v[68:71], v[2:5], 0
	v_mfma_f32_16x16x32_bf16 v[68:71], v[72:75], v[6:9], v[68:71]
	v_mul_f32_e32 v72, 0x3e38aa3b, v57
	v_max3_f32 v55, v55, s88, v72
	v_mul_f32_e32 v72, 0x3e38aa3b, v58
	v_mul_f32_e32 v73, 0x3e38aa3b, v59
	v_max3_f32 v55, v55, v72, v73
	v_mul_f32_e32 v72, 0x3e38aa3b, v60
	v_mul_f32_e32 v73, 0x3e38aa3b, v61
	v_max3_f32 v55, v55, v72, v73
	v_mul_f32_e32 v72, 0x3e38aa3b, v62
	v_mul_f32_e32 v73, 0x3e38aa3b, v63
	v_max3_f32 v55, v55, v72, v73
	v_mul_f32_e32 v72, 0x3e38aa3b, v64
	v_mul_f32_e32 v73, 0x3e38aa3b, v65
	v_max3_f32 v55, v55, v72, v73
	v_mul_f32_e32 v72, 0x3e38aa3b, v66
	v_mul_f32_e32 v73, 0x3e38aa3b, v67
	v_max3_f32 v55, v55, v72, v73
	v_mul_f32_e32 v72, 0x3e38aa3b, v68
	v_mul_f32_e32 v73, 0x3e38aa3b, v69
	v_max3_f32 v55, v55, v72, v73
	v_mul_f32_e32 v72, 0x3e38aa3b, v70
	v_mul_f32_e32 v73, 0x3e38aa3b, v71
	v_max3_f32 v55, v55, v72, v73
	v_mov_b32_e32 v252, v55
	v_mov_b32_e32 v253, v55
	s_nop 1
	v_permlane16_swap_b32_e32 v252, v253
	s_waitcnt lgkmcnt(0)
	v_max_f32_e32 v55, v252, v253
	v_mov_b32_e32 v254, v55
	v_mov_b32_e32 v255, v55
	s_nop 1
	v_permlane32_swap_b32_e32 v254, v255
	s_waitcnt lgkmcnt(0)
	v_max3_f32 v55, v52, v254, v255
	v_sub_f32_e32 v52, v52, v55
	v_fma_f32 v56, v56, s91, -v55
	v_fma_f32 v57, v57, s91, -v55
	v_fma_f32 v58, v58, s91, -v55
	v_fma_f32 v59, v59, s91, -v55
	v_fma_f32 v60, v60, s91, -v55
	v_fma_f32 v61, v61, s91, -v55
	v_fma_f32 v62, v62, s91, -v55
	v_fma_f32 v63, v63, s91, -v55
	v_exp_f32_e32 v52, v52
	v_exp_f32_e32 v56, v56
	v_exp_f32_e32 v57, v57
	v_exp_f32_e32 v58, v58
	v_exp_f32_e32 v59, v59
	v_exp_f32_e32 v60, v60
	v_exp_f32_e32 v61, v61
	v_exp_f32_e32 v62, v62
	v_exp_f32_e32 v63, v63
	v_pk_mul_f32 v[28:29], v[28:29], v[52:53] op_sel_hi:[1,0]
	v_pk_mul_f32 v[26:27], v[26:27], v[52:53] op_sel_hi:[1,0]
	v_cvt_pk_bf16_f32 v72, v56, v57
	v_cvt_pk_bf16_f32 v73, v58, v59
	v_cvt_pk_bf16_f32 v74, v60, v61
	v_cvt_pk_bf16_f32 v75, v62, v63
	v_fma_f32 v64, v64, s91, -v55
	v_fma_f32 v65, v65, s91, -v55
	v_mfma_f32_16x16x32_bf16 v[26:29], v[80:83], v[72:75], v[26:29]
	ds_read_b128 v[80:83], v84 offset:9280
	v_fma_f32 v66, v66, s91, -v55
	v_fma_f32 v67, v67, s91, -v55
	v_fma_f32 v68, v68, s91, -v55
	v_fma_f32 v69, v69, s91, -v55
	v_fma_f32 v70, v70, s91, -v55
	v_fma_f32 v71, v71, s91, -v55
	v_exp_f32_e32 v64, v64
	v_exp_f32_e32 v65, v65
	v_exp_f32_e32 v66, v66
	v_exp_f32_e32 v67, v67
	v_exp_f32_e32 v68, v68
	v_exp_f32_e32 v69, v69
	v_exp_f32_e32 v70, v70
	v_exp_f32_e32 v71, v71
	v_cvt_pk_bf16_f32 v76, v64, v65
	v_cvt_pk_bf16_f32 v77, v66, v67
	v_cvt_pk_bf16_f32 v78, v68, v69
	v_cvt_pk_bf16_f32 v79, v70, v71
	v_pk_mul_f32 v[32:33], v[32:33], v[52:53] op_sel_hi:[1,0]
	v_pk_mul_f32 v[30:31], v[30:31], v[52:53] op_sel_hi:[1,0]
	s_waitcnt lgkmcnt(0)
	v_mfma_f32_16x16x32_bf16 v[26:29], v[80:83], v[76:79], v[26:29]
	v_pk_mul_f32 v[36:37], v[36:37], v[52:53] op_sel_hi:[1,0]
	v_pk_mul_f32 v[34:35], v[34:35], v[52:53] op_sel_hi:[1,0]
	s_waitcnt lgkmcnt(6)
	v_mfma_f32_16x16x32_bf16 v[30:33], v[210:213], v[72:75], v[30:33]
	v_pk_mul_f32 v[40:41], v[40:41], v[52:53] op_sel_hi:[1,0]
	v_pk_mul_f32 v[38:39], v[38:39], v[52:53] op_sel_hi:[1,0]
	s_waitcnt lgkmcnt(5)
	v_mfma_f32_16x16x32_bf16 v[30:33], v[214:217], v[76:79], v[30:33]
	s_waitcnt lgkmcnt(4)
	v_mfma_f32_16x16x32_bf16 v[34:37], v[218:221], v[72:75], v[34:37]
	s_waitcnt lgkmcnt(3)
	v_mfma_f32_16x16x32_bf16 v[34:37], v[222:225], v[76:79], v[34:37]
	s_waitcnt lgkmcnt(2)
	v_mfma_f32_16x16x32_bf16 v[38:41], v[226:229], v[72:75], v[38:41]
	s_waitcnt lgkmcnt(1)
	v_mfma_f32_16x16x32_bf16 v[38:41], v[230:233], v[76:79], v[38:41]
	s_cbranch_vccnz .LBB0_1165
	s_bitcmp1_b32 s12, 0
	s_cselect_b32 s13, 0x4800, 0
	v_add_u32_e32 v72, s13, v46
	s_waitcnt vmcnt(3)
	ds_write_b128 v72, v[14:17]
	s_waitcnt vmcnt(2)
	ds_write_b128 v72, v[10:13] offset:16
	s_waitcnt vmcnt(0)
	ds_write_b128 v72, v[22:25] offset:9216
	ds_write_b128 v72, v[18:21] offset:9232

.LBB0_1173:
	s_add_i32 s68, s12, 1
	s_bitcmp1_b32 s12, 0
	s_cselect_b32 s12, 0x4800, 0
	v_or_b32_e32 v99, s12, v74
	v_add_u32_e32 v93, v99, v81
	ds_read_b128 v[62:65], v93
	ds_read_b128 v[66:69], v93 offset:576
	ds_read_b128 v[70:73], v93 offset:4608
	ds_read_b128 v[88:91], v93 offset:5184
	s_andn2_b64 vcc, exec, s[60:61]
	s_waitcnt vmcnt(1) lgkmcnt(3)
	v_mfma_f32_16x16x32_bf16 v[62:65], v[62:65], v[50:53], 0
	s_waitcnt lgkmcnt(2)
	v_mfma_f32_16x16x32_bf16 v[66:69], v[66:69], v[50:53], 0
	s_nop 5
	v_mul_f32_e32 v59, 0x3e8293ee, v62
	v_mul_f32_e32 v60, 0x3e8293ee, v63
	v_max3_f32 v59, v59, s88, v60
	s_waitcnt lgkmcnt(1)
	v_mfma_f32_16x16x32_bf16 v[70:73], v[70:73], v[50:53], 0
	v_mul_f32_e32 v60, 0x3e8293ee, v64
	s_waitcnt lgkmcnt(0)
	v_mfma_f32_16x16x32_bf16 v[122:125], v[88:91], v[50:53], 0
	v_mul_f32_e32 v88, 0x3e8293ee, v65
	v_max3_f32 v59, v59, v60, v88
	v_mul_f32_e32 v60, 0x3e8293ee, v66
	v_mul_f32_e32 v88, 0x3e8293ee, v67
	v_max3_f32 v59, v59, v60, v88
	v_mul_f32_e32 v60, 0x3e8293ee, v68
	v_mul_f32_e32 v88, 0x3e8293ee, v69
	v_max3_f32 v59, v59, v60, v88
	v_mul_f32_e32 v60, 0x3e8293ee, v70
	v_mul_f32_e32 v88, 0x3e8293ee, v71
	v_max3_f32 v59, v59, v60, v88
	v_mul_f32_e32 v60, 0x3e8293ee, v72
	v_mul_f32_e32 v88, 0x3e8293ee, v73
	v_max3_f32 v59, v59, v60, v88
	v_mul_f32_e32 v60, 0x3e8293ee, v122
	v_mul_f32_e32 v88, 0x3e8293ee, v123
	v_max3_f32 v59, v59, v60, v88
	v_mul_f32_e32 v60, 0x3e8293ee, v124
	v_mul_f32_e32 v88, 0x3e8293ee, v125
	v_max3_f32 v59, v59, v60, v88
	v_mov_b32_e32 v252, v59
	v_mov_b32_e32 v253, v59
	s_nop 1
	v_permlane16_swap_b32_e32 v252, v253
	s_waitcnt lgkmcnt(0)
	v_max_f32_e32 v59, v252, v253
	v_mov_b32_e32 v254, v59
	v_mov_b32_e32 v255, v59
	s_nop 1
	v_permlane32_swap_b32_e32 v254, v255
	s_waitcnt lgkmcnt(0)
	v_max3_f32 v114, v58, v254, v255
	v_fma_f32 v59, v62, s89, -v114
	v_exp_f32_e32 v115, v59
	v_fma_f32 v59, v63, s89, -v114
	v_exp_f32_e32 v116, v59
	v_fma_f32 v59, v64, s89, -v114
	v_exp_f32_e32 v117, v59
	v_fma_f32 v59, v65, s89, -v114
	v_exp_f32_e32 v118, v59
	v_fma_f32 v59, v66, s89, -v114
	v_exp_f32_e32 v119, v59
	v_fma_f32 v59, v67, s89, -v114
	v_exp_f32_e32 v120, v59
	v_fma_f32 v59, v68, s89, -v114
	v_exp_f32_e32 v96, v59
	v_fma_f32 v59, v69, s89, -v114
	v_exp_f32_e32 v110, v59
	v_fma_f32 v59, v70, s89, -v114
	v_exp_f32_e32 v94, v59
	v_fma_f32 v59, v71, s89, -v114
	ds_read_b128 v[62:65], v93 offset:64
	ds_read_b128 v[66:69], v93 offset:640
	v_exp_f32_e32 v108, v59
	v_fma_f32 v59, v72, s89, -v114
	v_exp_f32_e32 v92, v59
	v_fma_f32 v59, v73, s89, -v114
	v_exp_f32_e32 v104, v59
	v_fma_f32 v59, v122, s89, -v114
	v_exp_f32_e32 v90, v59
	v_fma_f32 v59, v123, s89, -v114
	ds_read_b128 v[70:73], v93 offset:4672
	v_exp_f32_e32 v102, v59
	v_fma_f32 v59, v124, s89, -v114
	v_exp_f32_e32 v88, v59
	v_fma_f32 v59, v125, s89, -v114
	ds_read_b128 v[122:125], v93 offset:5248
	s_waitcnt vmcnt(0) lgkmcnt(3)
	v_mfma_f32_16x16x32_bf16 v[62:65], v[62:65], v[54:57], 0
	v_sub_f32_e32 v58, v58, v114
	v_exp_f32_e32 v98, v58
	v_exp_f32_e32 v100, v59
	s_waitcnt lgkmcnt(2)
	v_mfma_f32_16x16x32_bf16 v[66:69], v[66:69], v[54:57], 0
	v_cvt_pk_bf16_f32 v58, v115, v116
	s_nop 1
	v_mul_f32_e32 v89, 0x3e8293ee, v62
	v_mul_f32_e32 v91, 0x3e8293ee, v63
	s_waitcnt lgkmcnt(1)
	v_mfma_f32_16x16x32_bf16 v[70:73], v[70:73], v[54:57], 0
	v_max3_f32 v89, v89, s88, v91
	v_mul_f32_e32 v91, 0x3e8293ee, v64
	v_mul_f32_e32 v93, 0x3e8293ee, v65
	s_waitcnt lgkmcnt(0)
	v_mfma_f32_16x16x32_bf16 v[128:131], v[122:125], v[54:57], 0
	v_max3_f32 v89, v89, v91, v93
	v_mul_f32_e32 v91, 0x3e8293ee, v66
	v_mul_f32_e32 v93, 0x3e8293ee, v67
	v_max3_f32 v89, v89, v91, v93
	v_mul_f32_e32 v91, 0x3e8293ee, v68
	v_mul_f32_e32 v93, 0x3e8293ee, v69
	v_max3_f32 v89, v89, v91, v93
	v_mul_f32_e32 v91, 0x3e8293ee, v70
	v_mul_f32_e32 v93, 0x3e8293ee, v71
	v_max3_f32 v89, v89, v91, v93
	v_mul_f32_e32 v91, 0x3e8293ee, v72
	v_mul_f32_e32 v93, 0x3e8293ee, v73
	v_max3_f32 v89, v89, v91, v93
	v_mul_f32_e32 v91, 0x3e8293ee, v128
	v_mul_f32_e32 v93, 0x3e8293ee, v129
	v_max3_f32 v89, v89, v91, v93
	v_mul_f32_e32 v91, 0x3e8293ee, v130
	v_mul_f32_e32 v93, 0x3e8293ee, v131
	v_max3_f32 v89, v89, v91, v93
	v_mov_b32_e32 v252, v89
	v_mov_b32_e32 v253, v89
	s_nop 1
	v_permlane16_swap_b32_e32 v252, v253
	v_pk_mul_f32 v[4:5], v[4:5], v[98:99] op_sel_hi:[1,0]
	v_pk_mul_f32 v[2:3], v[2:3], v[98:99] op_sel_hi:[1,0]
	v_pk_mul_f32 v[12:13], v[12:13], v[98:99] op_sel_hi:[1,0]
	v_pk_mul_f32 v[10:11], v[10:11], v[98:99] op_sel_hi:[1,0]
	s_waitcnt lgkmcnt(0)
	v_max_f32_e32 v89, v252, v253
	v_mov_b32_e32 v254, v89
	v_mov_b32_e32 v255, v89
	s_nop 1
	v_permlane32_swap_b32_e32 v254, v255
	v_pk_mul_f32 v[16:17], v[16:17], v[98:99] op_sel_hi:[1,0]
	v_pk_mul_f32 v[14:15], v[14:15], v[98:99] op_sel_hi:[1,0]
	v_cvt_pk_bf16_f32 v59, v117, v118
	v_cvt_pk_bf16_f32 v60, v119, v120
	s_waitcnt lgkmcnt(0)
	v_max3_f32 v121, v61, v254, v255
	v_fma_f32 v62, v62, s89, -v121
	v_exp_f32_e32 v122, v62
	v_fma_f32 v62, v63, s89, -v121
	v_exp_f32_e32 v123, v62
	v_fma_f32 v62, v64, s89, -v121
	v_exp_f32_e32 v124, v62
	v_fma_f32 v62, v65, s89, -v121
	v_exp_f32_e32 v125, v62
	v_fma_f32 v62, v66, s89, -v121
	v_exp_f32_e32 v126, v62
	v_fma_f32 v62, v67, s89, -v121
	v_exp_f32_e32 v127, v62
	v_fma_f32 v62, v68, s89, -v121
	v_exp_f32_e32 v97, v62
	v_fma_f32 v62, v69, s89, -v121
	v_exp_f32_e32 v111, v62
	v_fma_f32 v62, v70, s89, -v121
	v_exp_f32_e32 v95, v62
	v_fma_f32 v62, v71, s89, -v121
	v_exp_f32_e32 v109, v62
	v_fma_f32 v62, v72, s89, -v121
	v_exp_f32_e32 v93, v62
	v_fma_f32 v62, v73, s89, -v121
	v_exp_f32_e32 v105, v62
	v_fma_f32 v62, v128, s89, -v121
	v_exp_f32_e32 v91, v62
	v_fma_f32 v62, v129, s89, -v121
	v_exp_f32_e32 v103, v62
	v_fma_f32 v62, v130, s89, -v121
	v_exp_f32_e32 v89, v62
	v_fma_f32 v62, v131, s89, -v121
	v_exp_f32_e32 v101, v62
	v_pk_mul_f32 v[64:65], v[20:21], v[98:99] op_sel_hi:[1,0]
	v_pk_mul_f32 v[62:63], v[18:19], v[98:99] op_sel_hi:[1,0]
	v_add_u32_e32 v99, v99, v87
	ds_read_b128 v[210:213], v99 offset:9280
	ds_read_b128 v[214:217], v99 offset:11520
	ds_read_b128 v[218:221], v99 offset:11584
	ds_read_b128 v[222:225], v99 offset:13824
	ds_read_b128 v[226:229], v99 offset:13888
	ds_read_b128 v[230:233], v99 offset:16128
	ds_read_b128 v[234:237], v99 offset:16192
	ds_read_b128 v[128:131], v99 offset:9216
	v_sub_f32_e32 v61, v61, v121
	v_exp_f32_e32 v112, v61
	v_cvt_pk_bf16_f32 v61, v96, v110
	v_cvt_pk_bf16_f32 v70, v122, v123
	v_cvt_pk_bf16_f32 v71, v124, v125
	v_pk_mul_f32 v[8:9], v[8:9], v[112:113] op_sel_hi:[1,0]
	v_pk_mul_f32 v[6:7], v[6:7], v[112:113] op_sel_hi:[1,0]
	v_cvt_pk_bf16_f32 v72, v126, v127
	v_cvt_pk_bf16_f32 v73, v97, v111
	s_waitcnt lgkmcnt(0)
	v_mfma_f32_16x16x32_bf16 v[2:5], v[128:131], v[58:61], v[2:5]
	v_cvt_pk_bf16_f32 v18, v94, v108
	v_cvt_pk_bf16_f32 v19, v92, v104
	v_cvt_pk_bf16_f32 v20, v90, v102
	v_mfma_f32_16x16x32_bf16 v[6:9], v[128:131], v[70:73], v[6:9]
	v_cvt_pk_bf16_f32 v21, v88, v100
	v_pk_mul_f32 v[68:69], v[32:33], v[112:113] op_sel_hi:[1,0]
	v_pk_mul_f32 v[66:67], v[30:31], v[112:113] op_sel_hi:[1,0]
	v_cvt_pk_bf16_f32 v30, v95, v109
	v_cvt_pk_bf16_f32 v31, v93, v105
	v_cvt_pk_bf16_f32 v32, v91, v103
	v_cvt_pk_bf16_f32 v33, v89, v101
	s_waitcnt lgkmcnt(7)
	v_mfma_f32_16x16x32_bf16 v[2:5], v[210:213], v[18:21], v[2:5]
	v_mul_f32_e64 v24, v24, v112
	v_mul_f32_e64 v25, v25, v112
	v_pk_mul_f32 v[22:23], v[22:23], v[112:113] op_sel_hi:[1,0]
	v_pk_mul_f32 v[28:29], v[28:29], v[112:113] op_sel_hi:[1,0]
	v_mfma_f32_16x16x32_bf16 v[6:9], v[210:213], v[30:33], v[6:9]
	v_pk_mul_f32 v[26:27], v[26:27], v[112:113] op_sel_hi:[1,0]
	s_waitcnt lgkmcnt(6)
	v_mfma_f32_16x16x32_bf16 v[10:13], v[214:217], v[58:61], v[10:13]
	v_mfma_f32_16x16x32_bf16 v[22:25], v[214:217], v[70:73], v[22:25]
	s_waitcnt lgkmcnt(5)
	v_mfma_f32_16x16x32_bf16 v[10:13], v[218:221], v[18:21], v[10:13]
	v_mfma_f32_16x16x32_bf16 v[22:25], v[218:221], v[30:33], v[22:25]
	s_waitcnt lgkmcnt(4)
	v_mfma_f32_16x16x32_bf16 v[14:17], v[222:225], v[58:61], v[14:17]
	v_mfma_f32_16x16x32_bf16 v[26:29], v[222:225], v[70:73], v[26:29]
	s_waitcnt lgkmcnt(3)
	v_mfma_f32_16x16x32_bf16 v[14:17], v[226:229], v[18:21], v[14:17]
	v_mfma_f32_16x16x32_bf16 v[26:29], v[226:229], v[30:33], v[26:29]
	s_waitcnt lgkmcnt(2)
	v_mfma_f32_16x16x32_bf16 v[58:61], v[230:233], v[58:61], v[62:65]
	v_mfma_f32_16x16x32_bf16 v[62:65], v[230:233], v[70:73], v[66:69]
	s_nop 2
	s_waitcnt lgkmcnt(1)
	v_mfma_f32_16x16x32_bf16 v[18:21], v[234:237], v[18:21], v[58:61]
	v_mfma_f32_16x16x32_bf16 v[30:33], v[234:237], v[30:33], v[62:65]
	s_cbranch_vccnz .LBB0_1170
	s_bitcmp1_b32 s68, 0
	s_cselect_b32 s12, 0x4800, 0
	v_add_u32_e32 v58, s12, v80
	ds_write_b128 v58, v[34:37]
	ds_write_b128 v58, v[38:41] offset:16
	ds_write_b128 v58, v[42:45] offset:9216
	ds_write_b128 v58, v[46:49] offset:9232
	s_branch .LBB0_1170

.LBB0_1184:
	s_cmp_gt_u32 s14, 3
	s_cselect_b64 s[68:69], -1, 0
	s_bitcmp1_b32 s14, 0
	s_cselect_b32 s14, 0x4800, 0
	v_or_b32_e32 v87, s14, v57
	v_add_u32_e32 v76, v87, v55
	ds_read_b128 v[60:63], v76
	ds_read_b128 v[64:67], v76 offset:64
	s_waitcnt vmcnt(1) lgkmcnt(1)
	v_mfma_f32_16x16x32_bf16 v[60:63], v[60:63], v[2:5], 0
	ds_read_b128 v[68:71], v76 offset:640
	ds_read_b128 v[72:75], v76 offset:4672
	s_waitcnt vmcnt(0) lgkmcnt(2)
	v_mfma_f32_16x16x32_bf16 v[60:63], v[64:67], v[6:9], v[60:63]
	ds_read_b128 v[64:67], v76 offset:576
	s_waitcnt lgkmcnt(0)
	v_mfma_f32_16x16x32_bf16 v[64:67], v[64:67], v[2:5], 0
	s_nop 4
	v_mul_f32_e32 v60, 0x3e38aa3b, v60
	v_mfma_f32_16x16x32_bf16 v[64:67], v[68:71], v[6:9], v[64:67]
	ds_read_b128 v[68:71], v76 offset:4608
	s_waitcnt lgkmcnt(0)
	v_mfma_f32_16x16x32_bf16 v[68:71], v[68:71], v[2:5], 0
	v_mfma_f32_16x16x32_bf16 v[68:71], v[72:75], v[6:9], v[68:71]
	ds_read_b128 v[72:75], v76 offset:5184
	ds_read_b128 v[76:79], v76 offset:5248
	s_waitcnt lgkmcnt(1)
	v_mfma_f32_16x16x32_bf16 v[72:75], v[72:75], v[2:5], 0
	s_waitcnt lgkmcnt(0)
	v_mfma_f32_16x16x32_bf16 v[72:75], v[76:79], v[6:9], v[72:75]
	v_add_u32_e32 v76, s12, v58
	v_add_u32_e32 v77, 0xfffffe3f, v76
	v_cmp_gt_u32_e32 vcc, s36, v77
	s_and_b64 vcc, s[68:69], vcc
	s_nop 0
	v_cndmask_b32_e32 v77, v60, v150, vcc
	v_mul_f32_e32 v60, 0x3e38aa3b, v61
	v_add_u32_e32 v61, 0xfffffe40, v76
	v_cmp_gt_u32_e32 vcc, s36, v61
	s_and_b64 vcc, s[68:69], vcc
	v_mul_f32_e32 v61, 0x3e38aa3b, v62
	v_add_u32_e32 v62, 0xfffffe41, v76
	v_cndmask_b32_e32 v78, v60, v150, vcc
	v_cmp_gt_u32_e32 vcc, s36, v62
	s_and_b64 vcc, s[68:69], vcc
	v_add_u32_e32 v62, 0xfffffe42, v76
	v_cndmask_b32_e32 v79, v61, v150, vcc
	v_cmp_gt_u32_e32 vcc, s36, v62
	v_mul_f32_e32 v61, 0x3e38aa3b, v63
	s_and_b64 vcc, s[68:69], vcc
	v_cndmask_b32_e32 v80, v61, v150, vcc
	v_add_u32_e32 v61, 0xfffffe43, v76
	v_cmp_gt_u32_e32 vcc, s36, v61
	v_mul_f32_e32 v62, 0x3e38aa3b, v64
	s_and_b64 vcc, s[68:69], vcc
	v_cndmask_b32_e32 v81, v62, v150, vcc
	v_add_u32_e32 v62, 0xfffffe44, v76
	v_cmp_gt_u32_e32 vcc, s36, v62
	v_mul_f32_e32 v61, 0x3e38aa3b, v65
	s_and_b64 vcc, s[68:69], vcc
	v_add_u32_e32 v62, 0xfffffe45, v76
	v_cndmask_b32_e32 v82, v61, v150, vcc
	v_cmp_gt_u32_e32 vcc, s36, v62
	v_mul_f32_e32 v61, 0x3e38aa3b, v66
	s_and_b64 vcc, s[68:69], vcc
	v_add_u32_e32 v62, 0xfffffe46, v76
	v_cndmask_b32_e32 v83, v61, v150, vcc
	v_cmp_gt_u32_e32 vcc, s36, v62
	v_mul_f32_e32 v61, 0x3e38aa3b, v67
	s_and_b64 vcc, s[68:69], vcc
	v_cndmask_b32_e32 v84, v61, v150, vcc
	v_add_u32_e32 v61, 0xfffffe5f, v76
	v_cmp_gt_u32_e32 vcc, s36, v61
	v_mul_f32_e32 v62, 0x3e38aa3b, v68
	s_and_b64 vcc, s[68:69], vcc
	v_cndmask_b32_e32 v85, v62, v150, vcc
	v_add_u32_e32 v62, 0xfffffe60, v76
	v_cmp_gt_u32_e32 vcc, s36, v62
	v_mul_f32_e32 v61, 0x3e38aa3b, v69
	s_and_b64 vcc, s[68:69], vcc
	v_add_u32_e32 v62, 0xfffffe61, v76
	v_cndmask_b32_e32 v88, v61, v150, vcc
	v_cmp_gt_u32_e32 vcc, s36, v62
	v_mul_f32_e32 v61, 0x3e38aa3b, v70
	s_and_b64 vcc, s[68:69], vcc
	v_add_u32_e32 v62, 0xfffffe62, v76
	v_cndmask_b32_e32 v89, v61, v150, vcc
	v_cmp_gt_u32_e32 vcc, s36, v62
	v_mul_f32_e32 v61, 0x3e38aa3b, v71
	s_and_b64 vcc, s[68:69], vcc
	v_cndmask_b32_e32 v90, v61, v150, vcc
	v_add_u32_e32 v61, 0xfffffe63, v76
	v_cmp_gt_u32_e32 vcc, s36, v61
	v_mul_f32_e32 v62, 0x3e38aa3b, v72
	s_and_b64 vcc, s[68:69], vcc
	v_cndmask_b32_e32 v91, v62, v150, vcc
	v_add_u32_e32 v62, 0xfffffe64, v76
	v_max3_f32 v60, v77, s88, v78
	v_cmp_gt_u32_e32 vcc, s36, v62
	v_max3_f32 v60, v60, v79, v80
	v_mul_f32_e32 v61, 0x3e38aa3b, v73
	s_and_b64 vcc, s[68:69], vcc
	v_add_u32_e32 v62, 0xfffffe65, v76
	v_max3_f32 v60, v60, v81, v82
	v_cndmask_b32_e32 v92, v61, v150, vcc
	v_cmp_gt_u32_e32 vcc, s36, v62
	v_max3_f32 v60, v60, v83, v84
	v_mul_f32_e32 v61, 0x3e38aa3b, v74
	s_and_b64 vcc, s[68:69], vcc
	v_add_u32_e32 v62, 0xfffffe66, v76
	v_max3_f32 v60, v60, v85, v88
	v_cndmask_b32_e32 v93, v61, v150, vcc
	v_cmp_gt_u32_e32 vcc, s36, v62
	v_max3_f32 v60, v60, v89, v90
	v_mul_f32_e32 v61, 0x3e38aa3b, v75
	s_and_b64 vcc, s[68:69], vcc
	v_max3_f32 v60, v60, v91, v92
	v_cndmask_b32_e32 v76, v61, v150, vcc
	v_max3_f32 v60, v60, v93, v76
	v_mov_b32_e32 v252, v60
	v_mov_b32_e32 v253, v60
	s_nop 1
	v_permlane16_swap_b32_e32 v252, v253
	s_andn2_b64 vcc, exec, s[60:61]
	s_waitcnt lgkmcnt(0)
	v_max_f32_e32 v60, v252, v253
	v_mov_b32_e32 v254, v60
	v_mov_b32_e32 v255, v60
	s_nop 1
	v_permlane32_swap_b32_e32 v254, v255
	s_waitcnt lgkmcnt(0)
	v_max3_f32 v60, v52, v254, v255
	v_sub_f32_e32 v61, v77, v60
	v_add_u32_e32 v77, v87, v56
	ds_read_b128 v[210:213], v77 offset:11520
	ds_read_b128 v[214:217], v77 offset:11584
	ds_read_b128 v[218:221], v77 offset:13824
	ds_read_b128 v[222:225], v77 offset:13888
	ds_read_b128 v[226:229], v77 offset:16128
	ds_read_b128 v[230:233], v77 offset:16192
	v_sub_f32_e32 v70, v88, v60
	v_sub_f32_e32 v71, v89, v60
	v_sub_f32_e32 v72, v90, v60
	v_sub_f32_e32 v73, v91, v60
	ds_read_b128 v[88:91], v77 offset:9216
	v_sub_f32_e32 v52, v52, v60
	v_sub_f32_e32 v62, v78, v60
	v_sub_f32_e32 v63, v79, v60
	v_sub_f32_e32 v64, v80, v60
	v_sub_f32_e32 v65, v81, v60
	v_sub_f32_e32 v66, v82, v60
	v_sub_f32_e32 v67, v83, v60
	v_sub_f32_e32 v68, v84, v60
	v_exp_f32_e32 v52, v52
	v_exp_f32_e32 v61, v61
	v_exp_f32_e32 v62, v62
	v_exp_f32_e32 v63, v63
	v_exp_f32_e32 v64, v64
	v_exp_f32_e32 v65, v65
	v_exp_f32_e32 v66, v66
	v_exp_f32_e32 v67, v67
	v_exp_f32_e32 v68, v68
	v_pk_mul_f32 v[28:29], v[28:29], v[52:53] op_sel_hi:[1,0]
	v_pk_mul_f32 v[26:27], v[26:27], v[52:53] op_sel_hi:[1,0]
	v_cvt_pk_bf16_f32 v78, v61, v62
	v_cvt_pk_bf16_f32 v79, v63, v64
	v_cvt_pk_bf16_f32 v80, v65, v66
	v_cvt_pk_bf16_f32 v81, v67, v68
	v_sub_f32_e32 v69, v85, v60
	v_sub_f32_e32 v74, v92, v60
	s_waitcnt lgkmcnt(0)
	v_mfma_f32_16x16x32_bf16 v[26:29], v[88:91], v[78:81], v[26:29]
	ds_read_b128 v[88:91], v77 offset:9280
	v_sub_f32_e32 v75, v93, v60
	v_sub_f32_e32 v76, v76, v60
	v_exp_f32_e32 v69, v69
	v_exp_f32_e32 v70, v70
	v_exp_f32_e32 v71, v71
	v_exp_f32_e32 v72, v72
	v_exp_f32_e32 v73, v73
	v_exp_f32_e32 v74, v74
	v_exp_f32_e32 v75, v75
	v_exp_f32_e32 v76, v76
	v_cvt_pk_bf16_f32 v82, v69, v70
	v_cvt_pk_bf16_f32 v83, v71, v72
	v_cvt_pk_bf16_f32 v84, v73, v74
	v_cvt_pk_bf16_f32 v85, v75, v76
	v_pk_mul_f32 v[32:33], v[32:33], v[52:53] op_sel_hi:[1,0]
	v_pk_mul_f32 v[30:31], v[30:31], v[52:53] op_sel_hi:[1,0]
	s_waitcnt lgkmcnt(0)
	v_mfma_f32_16x16x32_bf16 v[26:29], v[88:91], v[82:85], v[26:29]
	v_pk_mul_f32 v[36:37], v[36:37], v[52:53] op_sel_hi:[1,0]
	v_pk_mul_f32 v[34:35], v[34:35], v[52:53] op_sel_hi:[1,0]
	s_waitcnt lgkmcnt(7)
	v_mfma_f32_16x16x32_bf16 v[30:33], v[210:213], v[78:81], v[30:33]
	v_pk_mul_f32 v[40:41], v[40:41], v[52:53] op_sel_hi:[1,0]
	v_pk_mul_f32 v[38:39], v[38:39], v[52:53] op_sel_hi:[1,0]
	s_waitcnt lgkmcnt(6)
	v_mfma_f32_16x16x32_bf16 v[30:33], v[214:217], v[82:85], v[30:33]
	s_waitcnt lgkmcnt(5)
	v_mfma_f32_16x16x32_bf16 v[34:37], v[218:221], v[78:81], v[34:37]
	s_waitcnt lgkmcnt(4)
	v_mfma_f32_16x16x32_bf16 v[34:37], v[222:225], v[82:85], v[34:37]
	s_waitcnt lgkmcnt(3)
	v_mfma_f32_16x16x32_bf16 v[38:41], v[226:229], v[78:81], v[38:41]
	s_waitcnt lgkmcnt(2)
	v_mfma_f32_16x16x32_bf16 v[38:41], v[230:233], v[82:85], v[38:41]
	s_cbranch_vccnz .LBB0_1186
	s_bitcmp1_b32 s13, 0
	s_cselect_b32 s14, 0x4800, 0
	v_add_u32_e32 v77, s14, v48
	ds_write_b128 v77, v[14:17]
	ds_write_b128 v77, v[10:13] offset:16
	ds_write_b128 v77, v[22:25] offset:9216
	ds_write_b128 v77, v[18:21] offset:9232

.LBB0_1205:
	s_bitcmp1_b32 s12, 0
	s_cselect_b32 s12, 0x4800, 0
	v_or_b32_e32 v99, s12, v74
	v_add_u32_e32 v93, v99, v77
	ds_read_b128 v[62:65], v93
	ds_read_b128 v[66:69], v93 offset:576
	ds_read_b128 v[70:73], v93 offset:4608
	ds_read_b128 v[88:91], v93 offset:5184
	s_andn2_b64 vcc, exec, s[60:61]
	s_waitcnt vmcnt(1) lgkmcnt(3)
	v_mfma_f32_16x16x32_bf16 v[62:65], v[62:65], v[34:37], 0
	s_waitcnt lgkmcnt(2)
	v_mfma_f32_16x16x32_bf16 v[66:69], v[66:69], v[34:37], 0
	s_nop 5
	v_mul_f32_e32 v59, 0x3e8293ee, v62
	v_mul_f32_e32 v60, 0x3e8293ee, v63
	v_max3_f32 v59, v59, s88, v60
	s_waitcnt lgkmcnt(1)
	v_mfma_f32_16x16x32_bf16 v[70:73], v[70:73], v[34:37], 0
	v_mul_f32_e32 v60, 0x3e8293ee, v64
	v_mul_f32_e32 v81, 0x3e8293ee, v65
	v_max3_f32 v59, v59, v60, v81
	s_waitcnt lgkmcnt(0)
	v_mfma_f32_16x16x32_bf16 v[122:125], v[88:91], v[34:37], 0
	v_mul_f32_e32 v60, 0x3e8293ee, v66
	v_mul_f32_e32 v81, 0x3e8293ee, v67
	v_max3_f32 v59, v59, v60, v81
	v_mul_f32_e32 v60, 0x3e8293ee, v68
	v_mul_f32_e32 v81, 0x3e8293ee, v69
	v_max3_f32 v59, v59, v60, v81
	v_mul_f32_e32 v60, 0x3e8293ee, v70
	v_mul_f32_e32 v81, 0x3e8293ee, v71
	v_max3_f32 v59, v59, v60, v81
	v_mul_f32_e32 v60, 0x3e8293ee, v72
	v_mul_f32_e32 v81, 0x3e8293ee, v73
	v_max3_f32 v59, v59, v60, v81
	v_mul_f32_e32 v60, 0x3e8293ee, v122
	v_mul_f32_e32 v81, 0x3e8293ee, v123
	v_max3_f32 v59, v59, v60, v81
	v_mul_f32_e32 v60, 0x3e8293ee, v124
	v_mul_f32_e32 v81, 0x3e8293ee, v125
	v_max3_f32 v59, v59, v60, v81
	v_mov_b32_e32 v252, v59
	v_mov_b32_e32 v253, v59
	s_nop 1
	v_permlane16_swap_b32_e32 v252, v253
	s_waitcnt lgkmcnt(0)
	v_max_f32_e32 v59, v252, v253
	v_mov_b32_e32 v254, v59
	v_mov_b32_e32 v255, v59
	s_nop 1
	v_permlane32_swap_b32_e32 v254, v255
	s_waitcnt lgkmcnt(0)
	v_max3_f32 v81, v58, v254, v255
	v_fma_f32 v59, v62, s89, -v81
	v_exp_f32_e32 v115, v59
	v_fma_f32 v59, v63, s89, -v81
	v_exp_f32_e32 v116, v59
	v_fma_f32 v59, v64, s89, -v81
	v_exp_f32_e32 v117, v59
	v_fma_f32 v59, v65, s89, -v81
	v_exp_f32_e32 v118, v59
	v_fma_f32 v59, v66, s89, -v81
	v_exp_f32_e32 v119, v59
	v_fma_f32 v59, v67, s89, -v81
	v_exp_f32_e32 v120, v59
	v_fma_f32 v59, v68, s89, -v81
	v_exp_f32_e32 v96, v59
	v_fma_f32 v59, v69, s89, -v81
	v_exp_f32_e32 v110, v59
	v_fma_f32 v59, v70, s89, -v81
	v_exp_f32_e32 v94, v59
	v_fma_f32 v59, v71, s89, -v81
	ds_read_b128 v[62:65], v93 offset:64
	ds_read_b128 v[66:69], v93 offset:640
	v_exp_f32_e32 v108, v59
	v_fma_f32 v59, v72, s89, -v81
	v_exp_f32_e32 v92, v59
	v_fma_f32 v59, v73, s89, -v81
	v_exp_f32_e32 v104, v59
	v_fma_f32 v59, v122, s89, -v81
	v_exp_f32_e32 v90, v59
	v_fma_f32 v59, v123, s89, -v81
	ds_read_b128 v[70:73], v93 offset:4672
	v_exp_f32_e32 v102, v59
	v_fma_f32 v59, v124, s89, -v81
	v_exp_f32_e32 v88, v59
	v_fma_f32 v59, v125, s89, -v81
	ds_read_b128 v[122:125], v93 offset:5248
	s_waitcnt vmcnt(0) lgkmcnt(3)
	v_mfma_f32_16x16x32_bf16 v[62:65], v[62:65], v[42:45], 0
	v_sub_f32_e32 v58, v58, v81
	v_exp_f32_e32 v98, v58
	v_exp_f32_e32 v100, v59
	s_waitcnt lgkmcnt(2)
	v_mfma_f32_16x16x32_bf16 v[66:69], v[66:69], v[42:45], 0
	v_cvt_pk_bf16_f32 v58, v115, v116
	s_nop 1
	v_mul_f32_e32 v89, 0x3e8293ee, v62
	v_mul_f32_e32 v91, 0x3e8293ee, v63
	s_waitcnt lgkmcnt(1)
	v_mfma_f32_16x16x32_bf16 v[70:73], v[70:73], v[42:45], 0
	v_max3_f32 v89, v89, s88, v91
	v_mul_f32_e32 v91, 0x3e8293ee, v64
	v_mul_f32_e32 v93, 0x3e8293ee, v65
	s_waitcnt lgkmcnt(0)
	v_mfma_f32_16x16x32_bf16 v[128:131], v[122:125], v[42:45], 0
	v_max3_f32 v89, v89, v91, v93
	v_mul_f32_e32 v91, 0x3e8293ee, v66
	v_mul_f32_e32 v93, 0x3e8293ee, v67
	v_max3_f32 v89, v89, v91, v93
	v_mul_f32_e32 v91, 0x3e8293ee, v68
	v_mul_f32_e32 v93, 0x3e8293ee, v69
	v_max3_f32 v89, v89, v91, v93
	v_mul_f32_e32 v91, 0x3e8293ee, v70
	v_mul_f32_e32 v93, 0x3e8293ee, v71
	v_max3_f32 v89, v89, v91, v93
	v_mul_f32_e32 v91, 0x3e8293ee, v72
	v_mul_f32_e32 v93, 0x3e8293ee, v73
	v_max3_f32 v89, v89, v91, v93
	v_mul_f32_e32 v91, 0x3e8293ee, v128
	v_mul_f32_e32 v93, 0x3e8293ee, v129
	v_max3_f32 v89, v89, v91, v93
	v_mul_f32_e32 v91, 0x3e8293ee, v130
	v_mul_f32_e32 v93, 0x3e8293ee, v131
	v_max3_f32 v89, v89, v91, v93
	v_mov_b32_e32 v252, v89
	v_mov_b32_e32 v253, v89
	s_nop 1
	v_permlane16_swap_b32_e32 v252, v253
	v_pk_mul_f32 v[8:9], v[8:9], v[98:99] op_sel_hi:[1,0]
	v_pk_mul_f32 v[6:7], v[6:7], v[98:99] op_sel_hi:[1,0]
	v_pk_mul_f32 v[12:13], v[12:13], v[98:99] op_sel_hi:[1,0]
	v_pk_mul_f32 v[10:11], v[10:11], v[98:99] op_sel_hi:[1,0]
	s_waitcnt lgkmcnt(0)
	v_max_f32_e32 v89, v252, v253
	v_mov_b32_e32 v254, v89
	v_mov_b32_e32 v255, v89
	s_nop 1
	v_permlane32_swap_b32_e32 v254, v255
	v_pk_mul_f32 v[20:21], v[20:21], v[98:99] op_sel_hi:[1,0]
	v_pk_mul_f32 v[18:19], v[18:19], v[98:99] op_sel_hi:[1,0]
	v_cvt_pk_bf16_f32 v59, v117, v118
	v_cvt_pk_bf16_f32 v60, v119, v120
	s_waitcnt lgkmcnt(0)
	v_max3_f32 v121, v61, v254, v255
	v_fma_f32 v62, v62, s89, -v121
	v_exp_f32_e32 v122, v62
	v_fma_f32 v62, v63, s89, -v121
	v_exp_f32_e32 v123, v62
	v_fma_f32 v62, v64, s89, -v121
	v_exp_f32_e32 v124, v62
	v_fma_f32 v62, v65, s89, -v121
	v_exp_f32_e32 v125, v62
	v_fma_f32 v62, v66, s89, -v121
	v_exp_f32_e32 v126, v62
	v_fma_f32 v62, v67, s89, -v121
	v_exp_f32_e32 v127, v62
	v_fma_f32 v62, v68, s89, -v121
	v_exp_f32_e32 v97, v62
	v_fma_f32 v62, v69, s89, -v121
	v_exp_f32_e32 v111, v62
	v_fma_f32 v62, v70, s89, -v121
	v_exp_f32_e32 v95, v62
	v_fma_f32 v62, v71, s89, -v121
	v_exp_f32_e32 v109, v62
	v_fma_f32 v62, v72, s89, -v121
	v_exp_f32_e32 v93, v62
	v_fma_f32 v62, v73, s89, -v121
	v_exp_f32_e32 v105, v62
	v_fma_f32 v62, v128, s89, -v121
	v_exp_f32_e32 v91, v62
	v_fma_f32 v62, v129, s89, -v121
	v_exp_f32_e32 v103, v62
	v_fma_f32 v62, v130, s89, -v121
	v_exp_f32_e32 v89, v62
	v_fma_f32 v62, v131, s89, -v121
	v_exp_f32_e32 v101, v62
	v_pk_mul_f32 v[64:65], v[28:29], v[98:99] op_sel_hi:[1,0]
	v_pk_mul_f32 v[62:63], v[26:27], v[98:99] op_sel_hi:[1,0]
	v_add_u32_e32 v99, v99, v87
	ds_read_b128 v[210:213], v99 offset:9280
	ds_read_b128 v[214:217], v99 offset:11520
	ds_read_b128 v[218:221], v99 offset:11584
	ds_read_b128 v[222:225], v99 offset:13824
	ds_read_b128 v[226:229], v99 offset:13888
	ds_read_b128 v[230:233], v99 offset:16128
	ds_read_b128 v[234:237], v99 offset:16192
	ds_read_b128 v[128:131], v99 offset:9216
	v_sub_f32_e32 v61, v61, v121
	v_exp_f32_e32 v112, v61
	v_cvt_pk_bf16_f32 v61, v96, v110
	v_cvt_pk_bf16_f32 v70, v122, v123
	v_cvt_pk_bf16_f32 v71, v124, v125
	v_pk_mul_f32 v[4:5], v[4:5], v[112:113] op_sel_hi:[1,0]
	v_pk_mul_f32 v[2:3], v[2:3], v[112:113] op_sel_hi:[1,0]
	v_cvt_pk_bf16_f32 v72, v126, v127
	v_cvt_pk_bf16_f32 v73, v97, v111
	s_waitcnt lgkmcnt(0)
	v_mfma_f32_16x16x32_bf16 v[6:9], v[128:131], v[58:61], v[6:9]
	v_cvt_pk_bf16_f32 v26, v94, v108
	v_cvt_pk_bf16_f32 v27, v92, v104
	v_cvt_pk_bf16_f32 v28, v90, v102
	v_mfma_f32_16x16x32_bf16 v[2:5], v[128:131], v[70:73], v[2:5]
	v_cvt_pk_bf16_f32 v29, v88, v100
	v_pk_mul_f32 v[68:69], v[32:33], v[112:113] op_sel_hi:[1,0]
	v_pk_mul_f32 v[66:67], v[30:31], v[112:113] op_sel_hi:[1,0]
	v_cvt_pk_bf16_f32 v30, v95, v109
	v_cvt_pk_bf16_f32 v31, v93, v105
	v_cvt_pk_bf16_f32 v32, v91, v103
	v_cvt_pk_bf16_f32 v33, v89, v101
	s_waitcnt lgkmcnt(7)
	v_mfma_f32_16x16x32_bf16 v[6:9], v[210:213], v[26:29], v[6:9]
	v_mul_f32_e64 v16, v16, v112
	v_mul_f32_e64 v17, v17, v112
	v_pk_mul_f32 v[14:15], v[14:15], v[112:113] op_sel_hi:[1,0]
	v_pk_mul_f32 v[24:25], v[24:25], v[112:113] op_sel_hi:[1,0]
	v_mfma_f32_16x16x32_bf16 v[2:5], v[210:213], v[30:33], v[2:5]
	v_pk_mul_f32 v[22:23], v[22:23], v[112:113] op_sel_hi:[1,0]
	s_waitcnt lgkmcnt(6)
	v_mfma_f32_16x16x32_bf16 v[10:13], v[214:217], v[58:61], v[10:13]
	v_mfma_f32_16x16x32_bf16 v[14:17], v[214:217], v[70:73], v[14:17]
	s_waitcnt lgkmcnt(5)
	v_mfma_f32_16x16x32_bf16 v[10:13], v[218:221], v[26:29], v[10:13]
	v_mfma_f32_16x16x32_bf16 v[14:17], v[218:221], v[30:33], v[14:17]
	s_waitcnt lgkmcnt(4)
	v_mfma_f32_16x16x32_bf16 v[18:21], v[222:225], v[58:61], v[18:21]
	v_mfma_f32_16x16x32_bf16 v[22:25], v[222:225], v[70:73], v[22:25]
	s_waitcnt lgkmcnt(3)
	v_mfma_f32_16x16x32_bf16 v[18:21], v[226:229], v[26:29], v[18:21]
	v_mfma_f32_16x16x32_bf16 v[22:25], v[226:229], v[30:33], v[22:25]
	s_waitcnt lgkmcnt(2)
	v_mfma_f32_16x16x32_bf16 v[58:61], v[230:233], v[58:61], v[62:65]
	v_mfma_f32_16x16x32_bf16 v[62:65], v[230:233], v[70:73], v[66:69]
	s_nop 2
	s_waitcnt lgkmcnt(1)
	v_mfma_f32_16x16x32_bf16 v[26:29], v[234:237], v[26:29], v[58:61]
	v_mfma_f32_16x16x32_bf16 v[30:33], v[234:237], v[30:33], v[62:65]
	s_cbranch_vccnz .LBB0_1202
	s_bitcmp1_b32 s68, 0
	s_cselect_b32 s12, 0x4800, 0
	v_add_u32_e32 v58, s12, v80
	ds_write_b128 v58, v[46:49]
	ds_write_b128 v58, v[38:41] offset:16
	ds_write_b128 v58, v[54:57] offset:9216
	ds_write_b128 v58, v[50:53] offset:9232
	s_branch .LBB0_1202
